# GEMM K-loops: the vmcnt(8)/lgkmcnt(0) wait pairs merged into one s_waitcnt each (on top of v63)
# speedup vs baseline: 1.0041x; 1.0041x over previous
.LBB0_205:
	s_add_u32 s16, s42, 0xfff80080
	s_addc_u32 s17, s43, -1
	s_add_i32 s89, 0, 0x10000
	s_cmp_eq_u32 s88, 28
	s_cselect_b32 s45, s27, s17
	s_cselect_b32 s44, s73, s16
	s_cselect_b32 s29, s23, s78
	s_cselect_b32 s28, s74, s77
	s_add_i32 s91, 0, 0x14000
	ds_read_b128 v[132:135], v216
	ds_read_b128 v[136:139], v216 offset:1024
	ds_read_b128 v[140:143], v216 offset:2048
	ds_read_b128 v[144:147], v216 offset:3072
	ds_read_b128 v[148:151], v217
	ds_read_b128 v[152:155], v217 offset:1024
	ds_read_b128 v[166:169], v217 offset:2048
	ds_read_b128 v[170:173], v217 offset:3072
	s_add_i32 m0, s31, 0xc000
	ds_read_b128 v[184:187], v229
	ds_read_b128 v[188:191], v229 offset:1024
	ds_read_b128 v[192:195], v229 offset:2048
	ds_read_b128 v[196:199], v229 offset:3072
	ds_read_b128 v[200:203], v229 offset:4096
	ds_read_b128 v[204:207], v229 offset:5120
	ds_read_b128 v[208:211], v229 offset:6144
	ds_read_b128 v[212:215], v229 offset:7168
	global_load_lds_dwordx4 v162, s[42:43]
	s_add_i32 m0, s31, 0xe000
	s_nop 0
	global_load_lds_dwordx4 v164, s[42:43]
	s_waitcnt vmcnt(8) lgkmcnt(0)


	s_barrier
	v_mfma_f32_16x16x32_bf16 v[128:131], v[132:135], v[184:187], v[128:131]
	v_mfma_f32_16x16x32_bf16 v[124:127], v[140:143], v[184:187], v[124:127]
	v_mfma_f32_16x16x32_bf16 v[112:115], v[132:135], v[192:195], v[112:115]
	v_mfma_f32_16x16x32_bf16 v[108:111], v[140:143], v[192:195], v[108:111]
	v_mfma_f32_16x16x32_bf16 v[96:99], v[132:135], v[200:203], v[96:99]
	v_mfma_f32_16x16x32_bf16 v[92:95], v[140:143], v[200:203], v[92:95]
	v_mfma_f32_16x16x32_bf16 v[80:83], v[132:135], v[208:211], v[80:83]
	v_mfma_f32_16x16x32_bf16 v[76:79], v[140:143], v[208:211], v[76:79]
	v_mfma_f32_16x16x32_bf16 v[128:131], v[136:139], v[188:191], v[128:131]
	v_mfma_f32_16x16x32_bf16 v[124:127], v[144:147], v[188:191], v[124:127]
	v_mfma_f32_16x16x32_bf16 v[112:115], v[136:139], v[196:199], v[112:115]
	v_mfma_f32_16x16x32_bf16 v[108:111], v[144:147], v[196:199], v[108:111]
	v_mfma_f32_16x16x32_bf16 v[96:99], v[136:139], v[204:207], v[96:99]
	v_mfma_f32_16x16x32_bf16 v[92:95], v[144:147], v[204:207], v[92:95]
	v_mfma_f32_16x16x32_bf16 v[80:83], v[136:139], v[212:215], v[80:83]
	v_mfma_f32_16x16x32_bf16 v[76:79], v[144:147], v[212:215], v[76:79]
	v_mfma_f32_16x16x32_bf16 v[120:123], v[148:151], v[184:187], v[120:123]
	v_mfma_f32_16x16x32_bf16 v[116:119], v[166:169], v[184:187], v[116:119]
	v_mfma_f32_16x16x32_bf16 v[104:107], v[148:151], v[192:195], v[104:107]
	v_mfma_f32_16x16x32_bf16 v[100:103], v[166:169], v[192:195], v[100:103]
	v_mfma_f32_16x16x32_bf16 v[88:91], v[148:151], v[200:203], v[88:91]
	v_mfma_f32_16x16x32_bf16 v[84:87], v[166:169], v[200:203], v[84:87]
	v_mfma_f32_16x16x32_bf16 v[72:75], v[148:151], v[208:211], v[72:75]
	v_mfma_f32_16x16x32_bf16 v[68:71], v[166:169], v[208:211], v[68:71]
	v_mfma_f32_16x16x32_bf16 v[120:123], v[152:155], v[188:191], v[120:123]
	v_mfma_f32_16x16x32_bf16 v[116:119], v[170:173], v[188:191], v[116:119]
	v_mfma_f32_16x16x32_bf16 v[104:107], v[152:155], v[196:199], v[104:107]
	v_mfma_f32_16x16x32_bf16 v[100:103], v[170:173], v[196:199], v[100:103]
	v_mfma_f32_16x16x32_bf16 v[88:91], v[152:155], v[204:207], v[88:91]
	v_mfma_f32_16x16x32_bf16 v[84:87], v[170:173], v[204:207], v[84:87]
	v_mfma_f32_16x16x32_bf16 v[72:75], v[152:155], v[212:215], v[72:75]
	v_mfma_f32_16x16x32_bf16 v[68:71], v[170:173], v[212:215], v[68:71]
	s_barrier

	s_add_i32 s16, s89, s3
	s_mov_b32 m0, s16
	ds_read_b128 v[184:187], v229 offset:16384
	ds_read_b128 v[188:191], v229 offset:17408
	ds_read_b128 v[192:195], v229 offset:18432
	ds_read_b128 v[196:199], v229 offset:19456
	ds_read_b128 v[200:203], v229 offset:20480
	ds_read_b128 v[204:207], v229 offset:21504
	ds_read_b128 v[208:211], v229 offset:22528
	ds_read_b128 v[212:215], v229 offset:23552
	global_load_lds_dwordx4 v2, s[28:29]
	s_add_i32 m0, s16, 0x2000
	s_add_u32 s16, s28, 0x80000
	s_addc_u32 s17, s29, 0
	s_add_i32 s89, s91, s3
	global_load_lds_dwordx4 v156, s[28:29]
	s_mov_b32 m0, s89
	s_nop 0
	global_load_lds_dwordx4 v2, s[16:17]
	s_add_i32 m0, s89, 0x2000
	s_nop 0
	global_load_lds_dwordx4 v156, s[16:17]
	s_mov_b32 m0, s31
	s_nop 0
	global_load_lds_dwordx4 v160, s[44:45]
	s_mov_b32 m0, s33
	s_nop 0
	global_load_lds_dwordx4 v158, s[44:45]
	s_waitcnt vmcnt(8) lgkmcnt(0)


	s_barrier
	v_mfma_f32_16x16x32_bf16 v[64:67], v[132:135], v[184:187], v[64:67]
	v_mfma_f32_16x16x32_bf16 v[60:63], v[140:143], v[184:187], v[60:63]
	v_mfma_f32_16x16x32_bf16 v[48:51], v[132:135], v[192:195], v[48:51]
	v_mfma_f32_16x16x32_bf16 v[44:47], v[140:143], v[192:195], v[44:47]
	v_mfma_f32_16x16x32_bf16 v[32:35], v[132:135], v[200:203], v[32:35]
	v_mfma_f32_16x16x32_bf16 v[28:31], v[140:143], v[200:203], v[28:31]
	v_mfma_f32_16x16x32_bf16 v[16:19], v[132:135], v[208:211], v[16:19]
	v_mfma_f32_16x16x32_bf16 v[12:15], v[140:143], v[208:211], v[12:15]
	v_mfma_f32_16x16x32_bf16 v[64:67], v[136:139], v[188:191], v[64:67]
	v_mfma_f32_16x16x32_bf16 v[60:63], v[144:147], v[188:191], v[60:63]
	v_mfma_f32_16x16x32_bf16 v[48:51], v[136:139], v[196:199], v[48:51]
	v_mfma_f32_16x16x32_bf16 v[44:47], v[144:147], v[196:199], v[44:47]
	v_mfma_f32_16x16x32_bf16 v[32:35], v[136:139], v[204:207], v[32:35]
	v_mfma_f32_16x16x32_bf16 v[28:31], v[144:147], v[204:207], v[28:31]
	v_mfma_f32_16x16x32_bf16 v[16:19], v[136:139], v[212:215], v[16:19]
	v_mfma_f32_16x16x32_bf16 v[12:15], v[144:147], v[212:215], v[12:15]
	v_mfma_f32_16x16x32_bf16 v[56:59], v[148:151], v[184:187], v[56:59]
	v_mfma_f32_16x16x32_bf16 v[52:55], v[166:169], v[184:187], v[52:55]
	v_mfma_f32_16x16x32_bf16 v[40:43], v[148:151], v[192:195], v[40:43]
	v_mfma_f32_16x16x32_bf16 v[36:39], v[166:169], v[192:195], v[36:39]
	v_mfma_f32_16x16x32_bf16 v[24:27], v[148:151], v[200:203], v[24:27]
	v_mfma_f32_16x16x32_bf16 v[20:23], v[166:169], v[200:203], v[20:23]
	v_mfma_f32_16x16x32_bf16 v[8:11], v[148:151], v[208:211], v[8:11]
	v_mfma_f32_16x16x32_bf16 v[4:7], v[166:169], v[208:211], v[4:7]
	v_mfma_f32_16x16x32_bf16 v[56:59], v[152:155], v[188:191], v[56:59]
	v_mfma_f32_16x16x32_bf16 v[52:55], v[170:173], v[188:191], v[52:55]
	v_mfma_f32_16x16x32_bf16 v[40:43], v[152:155], v[196:199], v[40:43]
	v_mfma_f32_16x16x32_bf16 v[36:39], v[170:173], v[196:199], v[36:39]
	v_mfma_f32_16x16x32_bf16 v[24:27], v[152:155], v[204:207], v[24:27]
	v_mfma_f32_16x16x32_bf16 v[20:23], v[170:173], v[204:207], v[20:23]
	v_mfma_f32_16x16x32_bf16 v[8:11], v[152:155], v[212:215], v[8:11]
	v_mfma_f32_16x16x32_bf16 v[4:7], v[170:173], v[212:215], v[4:7]
	s_barrier

	s_add_i32 s89, 0, 0x18000
	s_add_i32 s91, 0, 0x1c000
	ds_read_b128 v[132:135], v218
	ds_read_b128 v[136:139], v218 offset:1024
	ds_read_b128 v[140:143], v218 offset:2048
	ds_read_b128 v[144:147], v218 offset:3072
	ds_read_b128 v[148:151], v219
	ds_read_b128 v[152:155], v219 offset:1024
	ds_read_b128 v[166:169], v219 offset:2048
	ds_read_b128 v[170:173], v219 offset:3072
	s_add_u32 s16, s44, 0x80000
	s_addc_u32 s17, s45, 0
	s_mov_b32 m0, s46
	ds_read_b128 v[184:187], v229 offset:32768
	ds_read_b128 v[188:191], v229 offset:33792
	ds_read_b128 v[192:195], v229 offset:34816
	ds_read_b128 v[196:199], v229 offset:35840
	ds_read_b128 v[200:203], v229 offset:36864
	ds_read_b128 v[204:207], v229 offset:37888
	ds_read_b128 v[208:211], v229 offset:38912
	ds_read_b128 v[212:215], v229 offset:39936
	global_load_lds_dwordx4 v160, s[16:17]
	s_mov_b32 m0, s47
	s_nop 0
	global_load_lds_dwordx4 v158, s[16:17]
	s_waitcnt vmcnt(8) lgkmcnt(0)


	s_barrier
	v_mfma_f32_16x16x32_bf16 v[128:131], v[132:135], v[184:187], v[128:131]
	v_mfma_f32_16x16x32_bf16 v[124:127], v[140:143], v[184:187], v[124:127]
	v_mfma_f32_16x16x32_bf16 v[112:115], v[132:135], v[192:195], v[112:115]
	v_mfma_f32_16x16x32_bf16 v[108:111], v[140:143], v[192:195], v[108:111]
	v_mfma_f32_16x16x32_bf16 v[96:99], v[132:135], v[200:203], v[96:99]
	v_mfma_f32_16x16x32_bf16 v[92:95], v[140:143], v[200:203], v[92:95]
	v_mfma_f32_16x16x32_bf16 v[80:83], v[132:135], v[208:211], v[80:83]
	v_mfma_f32_16x16x32_bf16 v[76:79], v[140:143], v[208:211], v[76:79]
	v_mfma_f32_16x16x32_bf16 v[128:131], v[136:139], v[188:191], v[128:131]
	v_mfma_f32_16x16x32_bf16 v[124:127], v[144:147], v[188:191], v[124:127]
	v_mfma_f32_16x16x32_bf16 v[112:115], v[136:139], v[196:199], v[112:115]
	v_mfma_f32_16x16x32_bf16 v[108:111], v[144:147], v[196:199], v[108:111]
	v_mfma_f32_16x16x32_bf16 v[96:99], v[136:139], v[204:207], v[96:99]
	v_mfma_f32_16x16x32_bf16 v[92:95], v[144:147], v[204:207], v[92:95]
	v_mfma_f32_16x16x32_bf16 v[80:83], v[136:139], v[212:215], v[80:83]
	v_mfma_f32_16x16x32_bf16 v[76:79], v[144:147], v[212:215], v[76:79]
	v_mfma_f32_16x16x32_bf16 v[120:123], v[148:151], v[184:187], v[120:123]
	v_mfma_f32_16x16x32_bf16 v[116:119], v[166:169], v[184:187], v[116:119]
	v_mfma_f32_16x16x32_bf16 v[104:107], v[148:151], v[192:195], v[104:107]
	v_mfma_f32_16x16x32_bf16 v[100:103], v[166:169], v[192:195], v[100:103]
	v_mfma_f32_16x16x32_bf16 v[88:91], v[148:151], v[200:203], v[88:91]
	v_mfma_f32_16x16x32_bf16 v[84:87], v[166:169], v[200:203], v[84:87]
	v_mfma_f32_16x16x32_bf16 v[72:75], v[148:151], v[208:211], v[72:75]
	v_mfma_f32_16x16x32_bf16 v[68:71], v[166:169], v[208:211], v[68:71]
	v_mfma_f32_16x16x32_bf16 v[120:123], v[152:155], v[188:191], v[120:123]
	v_mfma_f32_16x16x32_bf16 v[116:119], v[170:173], v[188:191], v[116:119]
	v_mfma_f32_16x16x32_bf16 v[104:107], v[152:155], v[196:199], v[104:107]
	v_mfma_f32_16x16x32_bf16 v[100:103], v[170:173], v[196:199], v[100:103]
	v_mfma_f32_16x16x32_bf16 v[88:91], v[152:155], v[204:207], v[88:91]
	v_mfma_f32_16x16x32_bf16 v[84:87], v[170:173], v[204:207], v[84:87]
	v_mfma_f32_16x16x32_bf16 v[72:75], v[152:155], v[212:215], v[72:75]
	v_mfma_f32_16x16x32_bf16 v[68:71], v[170:173], v[212:215], v[68:71]
	s_barrier

	s_add_i32 s16, s89, s3
	s_mov_b32 m0, s16
	ds_read_b128 v[184:187], v229 offset:49152
	ds_read_b128 v[188:191], v229 offset:50176
	ds_read_b128 v[192:195], v229 offset:51200
	ds_read_b128 v[196:199], v229 offset:52224
	ds_read_b128 v[200:203], v229 offset:53248
	ds_read_b128 v[204:207], v229 offset:54272
	ds_read_b128 v[208:211], v229 offset:55296
	ds_read_b128 v[212:215], v229 offset:56320
	s_add_u32 s100, s28, s24
	s_addc_u32 s101, s29, s25
	global_load_lds_dwordx4 v2, s[100:101]
	s_add_i32 m0, s16, 0x2000
	s_add_u32 s16, s28, 0x80080
	s_addc_u32 s17, s29, 0
	s_add_i32 s28, s91, s3
	global_load_lds_dwordx4 v156, s[100:101]
	s_mov_b32 m0, s28
	s_nop 0
	global_load_lds_dwordx4 v2, s[16:17]
	s_add_i32 m0, s28, 0x2000
	s_nop 0
	global_load_lds_dwordx4 v156, s[16:17]
	s_mov_b32 m0, s48
	s_nop 0
	s_add_u32 s100, s44, s24
	s_addc_u32 s101, s45, s25
	global_load_lds_dwordx4 v160, s[100:101]
	s_mov_b32 m0, s49
	s_nop 0
	global_load_lds_dwordx4 v158, s[100:101]
	s_waitcnt vmcnt(8) lgkmcnt(0)


	s_barrier
	v_mfma_f32_16x16x32_bf16 v[64:67], v[132:135], v[184:187], v[64:67]
	v_mfma_f32_16x16x32_bf16 v[60:63], v[140:143], v[184:187], v[60:63]
	v_mfma_f32_16x16x32_bf16 v[48:51], v[132:135], v[192:195], v[48:51]
	v_mfma_f32_16x16x32_bf16 v[44:47], v[140:143], v[192:195], v[44:47]
	v_mfma_f32_16x16x32_bf16 v[32:35], v[132:135], v[200:203], v[32:35]
	v_mfma_f32_16x16x32_bf16 v[28:31], v[140:143], v[200:203], v[28:31]
	v_mfma_f32_16x16x32_bf16 v[16:19], v[132:135], v[208:211], v[16:19]
	v_mfma_f32_16x16x32_bf16 v[12:15], v[140:143], v[208:211], v[12:15]
	v_mfma_f32_16x16x32_bf16 v[64:67], v[136:139], v[188:191], v[64:67]
	v_mfma_f32_16x16x32_bf16 v[60:63], v[144:147], v[188:191], v[60:63]
	v_mfma_f32_16x16x32_bf16 v[48:51], v[136:139], v[196:199], v[48:51]
	v_mfma_f32_16x16x32_bf16 v[44:47], v[144:147], v[196:199], v[44:47]
	v_mfma_f32_16x16x32_bf16 v[32:35], v[136:139], v[204:207], v[32:35]
	v_mfma_f32_16x16x32_bf16 v[28:31], v[144:147], v[204:207], v[28:31]
	v_mfma_f32_16x16x32_bf16 v[16:19], v[136:139], v[212:215], v[16:19]
	v_mfma_f32_16x16x32_bf16 v[12:15], v[144:147], v[212:215], v[12:15]
	v_mfma_f32_16x16x32_bf16 v[56:59], v[148:151], v[184:187], v[56:59]
	v_mfma_f32_16x16x32_bf16 v[52:55], v[166:169], v[184:187], v[52:55]
	v_mfma_f32_16x16x32_bf16 v[40:43], v[148:151], v[192:195], v[40:43]
	v_mfma_f32_16x16x32_bf16 v[36:39], v[166:169], v[192:195], v[36:39]
	v_mfma_f32_16x16x32_bf16 v[24:27], v[148:151], v[200:203], v[24:27]
	v_mfma_f32_16x16x32_bf16 v[20:23], v[166:169], v[200:203], v[20:23]
	v_mfma_f32_16x16x32_bf16 v[8:11], v[148:151], v[208:211], v[8:11]
	v_mfma_f32_16x16x32_bf16 v[4:7], v[166:169], v[208:211], v[4:7]
	v_mfma_f32_16x16x32_bf16 v[56:59], v[152:155], v[188:191], v[56:59]
	v_mfma_f32_16x16x32_bf16 v[52:55], v[170:173], v[188:191], v[52:55]
	v_mfma_f32_16x16x32_bf16 v[40:43], v[152:155], v[196:199], v[40:43]
	v_mfma_f32_16x16x32_bf16 v[36:39], v[170:173], v[196:199], v[36:39]
	v_mfma_f32_16x16x32_bf16 v[24:27], v[152:155], v[204:207], v[24:27]
	v_mfma_f32_16x16x32_bf16 v[20:23], v[170:173], v[204:207], v[20:23]
	v_mfma_f32_16x16x32_bf16 v[8:11], v[152:155], v[212:215], v[8:11]
	v_mfma_f32_16x16x32_bf16 v[4:7], v[170:173], v[212:215], v[4:7]
	s_barrier

	s_add_i32 s88, s88, 2
	s_add_u32 s42, s42, 0x100
	s_addc_u32 s43, s43, 0
	s_add_u32 s77, s77, 0x100
	s_addc_u32 s78, s78, 0
	s_cmp_gt_u32 s88, 29
	s_cbranch_scc0 .LBB0_205
	s_setprio 0
	v_mov_b32_e32 v176, 0xc2000000

.LBB0_366:
	s_add_u32 s48, s50, 0x100
	s_addc_u32 s49, s51, 0
	s_add_i32 s16, 0, 0x10000
	s_cmpk_eq_i32 s22, 0x54
	s_cselect_b32 vcc_hi, s19, s49
	s_cselect_b32 vcc_lo, s18, s48
	s_cselect_b32 s29, s27, s33
	s_cselect_b32 s28, s26, s31
	s_add_i32 s23, 0, 0x14000
	ds_read_b128 v[132:135], v174
	ds_read_b128 v[136:139], v174 offset:1024
	ds_read_b128 v[140:143], v174 offset:2048
	ds_read_b128 v[144:147], v174 offset:3072
	ds_read_b128 v[148:151], v175
	ds_read_b128 v[152:155], v175 offset:1024
	ds_read_b128 v[156:159], v175 offset:2048
	ds_read_b128 v[160:163], v175 offset:3072
	s_add_i32 m0, s74, 0xc000
	ds_read_b128 v[164:167], v246
	ds_read_b128 v[188:191], v246 offset:1024
	ds_read_b128 v[192:195], v246 offset:2048
	ds_read_b128 v[196:199], v246 offset:3072
	ds_read_b128 v[200:203], v246 offset:4096
	ds_read_b128 v[204:207], v246 offset:5120
	ds_read_b128 v[208:211], v246 offset:6144
	ds_read_b128 v[212:215], v246 offset:7168
	global_load_lds_dwordx4 v184, s[50:51]
	s_add_i32 m0, s74, 0xe000
	s_nop 0
	global_load_lds_dwordx4 v186, s[50:51]
	s_waitcnt vmcnt(8) lgkmcnt(0)


	s_barrier
	v_mfma_f32_16x16x32_bf16 v[128:131], v[132:135], v[164:167], v[128:131]
	v_mfma_f32_16x16x32_bf16 v[124:127], v[140:143], v[164:167], v[124:127]
	v_mfma_f32_16x16x32_bf16 v[112:115], v[132:135], v[192:195], v[112:115]
	v_mfma_f32_16x16x32_bf16 v[108:111], v[140:143], v[192:195], v[108:111]
	v_mfma_f32_16x16x32_bf16 v[96:99], v[132:135], v[200:203], v[96:99]
	v_mfma_f32_16x16x32_bf16 v[92:95], v[140:143], v[200:203], v[92:95]
	v_mfma_f32_16x16x32_bf16 v[80:83], v[132:135], v[208:211], v[80:83]
	v_mfma_f32_16x16x32_bf16 v[76:79], v[140:143], v[208:211], v[76:79]
	v_mfma_f32_16x16x32_bf16 v[128:131], v[136:139], v[188:191], v[128:131]
	v_mfma_f32_16x16x32_bf16 v[124:127], v[144:147], v[188:191], v[124:127]
	v_mfma_f32_16x16x32_bf16 v[112:115], v[136:139], v[196:199], v[112:115]
	v_mfma_f32_16x16x32_bf16 v[108:111], v[144:147], v[196:199], v[108:111]
	v_mfma_f32_16x16x32_bf16 v[96:99], v[136:139], v[204:207], v[96:99]
	v_mfma_f32_16x16x32_bf16 v[92:95], v[144:147], v[204:207], v[92:95]
	v_mfma_f32_16x16x32_bf16 v[80:83], v[136:139], v[212:215], v[80:83]
	v_mfma_f32_16x16x32_bf16 v[76:79], v[144:147], v[212:215], v[76:79]
	v_mfma_f32_16x16x32_bf16 v[120:123], v[148:151], v[164:167], v[120:123]
	v_mfma_f32_16x16x32_bf16 v[116:119], v[156:159], v[164:167], v[116:119]
	v_mfma_f32_16x16x32_bf16 v[104:107], v[148:151], v[192:195], v[104:107]
	v_mfma_f32_16x16x32_bf16 v[100:103], v[156:159], v[192:195], v[100:103]
	v_mfma_f32_16x16x32_bf16 v[88:91], v[148:151], v[200:203], v[88:91]
	v_mfma_f32_16x16x32_bf16 v[84:87], v[156:159], v[200:203], v[84:87]
	v_mfma_f32_16x16x32_bf16 v[72:75], v[148:151], v[208:211], v[72:75]
	v_mfma_f32_16x16x32_bf16 v[68:71], v[156:159], v[208:211], v[68:71]
	v_mfma_f32_16x16x32_bf16 v[120:123], v[152:155], v[188:191], v[120:123]
	v_mfma_f32_16x16x32_bf16 v[116:119], v[160:163], v[188:191], v[116:119]
	v_mfma_f32_16x16x32_bf16 v[104:107], v[152:155], v[196:199], v[104:107]
	v_mfma_f32_16x16x32_bf16 v[100:103], v[160:163], v[196:199], v[100:103]
	v_mfma_f32_16x16x32_bf16 v[88:91], v[152:155], v[204:207], v[88:91]
	v_mfma_f32_16x16x32_bf16 v[84:87], v[160:163], v[204:207], v[84:87]
	v_mfma_f32_16x16x32_bf16 v[72:75], v[152:155], v[212:215], v[72:75]
	v_mfma_f32_16x16x32_bf16 v[68:71], v[160:163], v[212:215], v[68:71]
	s_barrier

	s_add_i32 s16, s16, s73
	s_mov_b32 m0, s16
	ds_read_b128 v[164:167], v246 offset:16384
	ds_read_b128 v[188:191], v246 offset:17408
	ds_read_b128 v[192:195], v246 offset:18432
	ds_read_b128 v[196:199], v246 offset:19456
	ds_read_b128 v[200:203], v246 offset:20480
	ds_read_b128 v[204:207], v246 offset:21504
	ds_read_b128 v[208:211], v246 offset:22528
	ds_read_b128 v[212:215], v246 offset:23552
	global_load_lds_dwordx4 v2, s[28:29]
	s_add_i32 m0, s16, 0x2000
	s_add_u32 s16, s28, 0x58000
	s_addc_u32 s17, s29, 0
	s_add_i32 s23, s23, s73
	global_load_lds_dwordx4 v168, s[28:29]
	s_mov_b32 m0, s23
	s_nop 0
	global_load_lds_dwordx4 v2, s[16:17]
	s_add_i32 m0, s23, 0x2000
	s_nop 0
	global_load_lds_dwordx4 v168, s[16:17]
	s_mov_b32 m0, s74
	s_nop 0
	global_load_lds_dwordx4 v172, vcc
	s_mov_b32 m0, s77
	s_nop 0
	global_load_lds_dwordx4 v170, vcc
	s_waitcnt vmcnt(8) lgkmcnt(0)


	s_barrier
	v_mfma_f32_16x16x32_bf16 v[64:67], v[132:135], v[164:167], v[64:67]
	v_mfma_f32_16x16x32_bf16 v[60:63], v[140:143], v[164:167], v[60:63]
	v_mfma_f32_16x16x32_bf16 v[48:51], v[132:135], v[192:195], v[48:51]
	v_mfma_f32_16x16x32_bf16 v[44:47], v[140:143], v[192:195], v[44:47]
	v_mfma_f32_16x16x32_bf16 v[32:35], v[132:135], v[200:203], v[32:35]
	v_mfma_f32_16x16x32_bf16 v[28:31], v[140:143], v[200:203], v[28:31]
	v_mfma_f32_16x16x32_bf16 v[16:19], v[132:135], v[208:211], v[16:19]
	v_mfma_f32_16x16x32_bf16 v[12:15], v[140:143], v[208:211], v[12:15]
	v_mfma_f32_16x16x32_bf16 v[64:67], v[136:139], v[188:191], v[64:67]
	v_mfma_f32_16x16x32_bf16 v[60:63], v[144:147], v[188:191], v[60:63]
	v_mfma_f32_16x16x32_bf16 v[48:51], v[136:139], v[196:199], v[48:51]
	v_mfma_f32_16x16x32_bf16 v[44:47], v[144:147], v[196:199], v[44:47]
	v_mfma_f32_16x16x32_bf16 v[32:35], v[136:139], v[204:207], v[32:35]
	v_mfma_f32_16x16x32_bf16 v[28:31], v[144:147], v[204:207], v[28:31]
	v_mfma_f32_16x16x32_bf16 v[16:19], v[136:139], v[212:215], v[16:19]
	v_mfma_f32_16x16x32_bf16 v[12:15], v[144:147], v[212:215], v[12:15]
	v_mfma_f32_16x16x32_bf16 v[56:59], v[148:151], v[164:167], v[56:59]
	v_mfma_f32_16x16x32_bf16 v[52:55], v[156:159], v[164:167], v[52:55]
	v_mfma_f32_16x16x32_bf16 v[40:43], v[148:151], v[192:195], v[40:43]
	v_mfma_f32_16x16x32_bf16 v[36:39], v[156:159], v[192:195], v[36:39]
	v_mfma_f32_16x16x32_bf16 v[24:27], v[148:151], v[200:203], v[24:27]
	v_mfma_f32_16x16x32_bf16 v[20:23], v[156:159], v[200:203], v[20:23]
	v_mfma_f32_16x16x32_bf16 v[8:11], v[148:151], v[208:211], v[8:11]
	v_mfma_f32_16x16x32_bf16 v[4:7], v[156:159], v[208:211], v[4:7]
	v_mfma_f32_16x16x32_bf16 v[56:59], v[152:155], v[188:191], v[56:59]
	v_mfma_f32_16x16x32_bf16 v[52:55], v[160:163], v[188:191], v[52:55]
	v_mfma_f32_16x16x32_bf16 v[40:43], v[152:155], v[196:199], v[40:43]
	v_mfma_f32_16x16x32_bf16 v[36:39], v[160:163], v[196:199], v[36:39]
	v_mfma_f32_16x16x32_bf16 v[24:27], v[152:155], v[204:207], v[24:27]
	v_mfma_f32_16x16x32_bf16 v[20:23], v[160:163], v[204:207], v[20:23]
	v_mfma_f32_16x16x32_bf16 v[8:11], v[152:155], v[212:215], v[8:11]
	v_mfma_f32_16x16x32_bf16 v[4:7], v[160:163], v[212:215], v[4:7]
	s_barrier

	s_add_i32 s23, 0, 0x18000
	s_add_i32 s50, 0, 0x1c000
	ds_read_b128 v[132:135], v182
	ds_read_b128 v[136:139], v182 offset:1024
	ds_read_b128 v[140:143], v182 offset:2048
	ds_read_b128 v[144:147], v182 offset:3072
	ds_read_b128 v[148:151], v183
	ds_read_b128 v[152:155], v183 offset:1024
	ds_read_b128 v[156:159], v183 offset:2048
	ds_read_b128 v[160:163], v183 offset:3072
	s_add_u32 s16, vcc_lo, 0x160000
	s_addc_u32 s17, vcc_hi, 0
	s_mov_b32 m0, s72
	ds_read_b128 v[164:167], v246 offset:32768
	ds_read_b128 v[188:191], v246 offset:33792
	ds_read_b128 v[192:195], v246 offset:34816
	ds_read_b128 v[196:199], v246 offset:35840
	ds_read_b128 v[200:203], v246 offset:36864
	ds_read_b128 v[204:207], v246 offset:37888
	ds_read_b128 v[208:211], v246 offset:38912
	ds_read_b128 v[212:215], v246 offset:39936
	global_load_lds_dwordx4 v172, s[16:17]
	s_mov_b32 m0, s78
	s_nop 0
	global_load_lds_dwordx4 v170, s[16:17]
	s_waitcnt vmcnt(8) lgkmcnt(0)


	s_barrier
	v_mfma_f32_16x16x32_bf16 v[128:131], v[132:135], v[164:167], v[128:131]
	v_mfma_f32_16x16x32_bf16 v[124:127], v[140:143], v[164:167], v[124:127]
	v_mfma_f32_16x16x32_bf16 v[112:115], v[132:135], v[192:195], v[112:115]
	v_mfma_f32_16x16x32_bf16 v[108:111], v[140:143], v[192:195], v[108:111]
	v_mfma_f32_16x16x32_bf16 v[96:99], v[132:135], v[200:203], v[96:99]
	v_mfma_f32_16x16x32_bf16 v[92:95], v[140:143], v[200:203], v[92:95]
	v_mfma_f32_16x16x32_bf16 v[80:83], v[132:135], v[208:211], v[80:83]
	v_mfma_f32_16x16x32_bf16 v[76:79], v[140:143], v[208:211], v[76:79]
	v_mfma_f32_16x16x32_bf16 v[128:131], v[136:139], v[188:191], v[128:131]
	v_mfma_f32_16x16x32_bf16 v[124:127], v[144:147], v[188:191], v[124:127]
	v_mfma_f32_16x16x32_bf16 v[112:115], v[136:139], v[196:199], v[112:115]
	v_mfma_f32_16x16x32_bf16 v[108:111], v[144:147], v[196:199], v[108:111]
	v_mfma_f32_16x16x32_bf16 v[96:99], v[136:139], v[204:207], v[96:99]
	v_mfma_f32_16x16x32_bf16 v[92:95], v[144:147], v[204:207], v[92:95]
	v_mfma_f32_16x16x32_bf16 v[80:83], v[136:139], v[212:215], v[80:83]
	v_mfma_f32_16x16x32_bf16 v[76:79], v[144:147], v[212:215], v[76:79]
	v_mfma_f32_16x16x32_bf16 v[120:123], v[148:151], v[164:167], v[120:123]
	v_mfma_f32_16x16x32_bf16 v[116:119], v[156:159], v[164:167], v[116:119]
	v_mfma_f32_16x16x32_bf16 v[104:107], v[148:151], v[192:195], v[104:107]
	v_mfma_f32_16x16x32_bf16 v[100:103], v[156:159], v[192:195], v[100:103]
	v_mfma_f32_16x16x32_bf16 v[88:91], v[148:151], v[200:203], v[88:91]
	v_mfma_f32_16x16x32_bf16 v[84:87], v[156:159], v[200:203], v[84:87]
	v_mfma_f32_16x16x32_bf16 v[72:75], v[148:151], v[208:211], v[72:75]
	v_mfma_f32_16x16x32_bf16 v[68:71], v[156:159], v[208:211], v[68:71]
	v_mfma_f32_16x16x32_bf16 v[120:123], v[152:155], v[188:191], v[120:123]
	v_mfma_f32_16x16x32_bf16 v[116:119], v[160:163], v[188:191], v[116:119]
	v_mfma_f32_16x16x32_bf16 v[104:107], v[152:155], v[196:199], v[104:107]
	v_mfma_f32_16x16x32_bf16 v[100:103], v[160:163], v[196:199], v[100:103]
	v_mfma_f32_16x16x32_bf16 v[88:91], v[152:155], v[204:207], v[88:91]
	v_mfma_f32_16x16x32_bf16 v[84:87], v[160:163], v[204:207], v[84:87]
	v_mfma_f32_16x16x32_bf16 v[72:75], v[152:155], v[212:215], v[72:75]
	v_mfma_f32_16x16x32_bf16 v[68:71], v[160:163], v[212:215], v[68:71]
	s_barrier

	s_add_i32 s16, s23, s73
	s_mov_b32 m0, s16
	ds_read_b128 v[164:167], v246 offset:49152
	ds_read_b128 v[188:191], v246 offset:50176
	ds_read_b128 v[192:195], v246 offset:51200
	ds_read_b128 v[196:199], v246 offset:52224
	ds_read_b128 v[200:203], v246 offset:53248
	ds_read_b128 v[204:207], v246 offset:54272
	ds_read_b128 v[208:211], v246 offset:55296
	ds_read_b128 v[212:215], v246 offset:56320
	s_add_u32 s100, s28, s24
	s_addc_u32 s101, s29, s25
	global_load_lds_dwordx4 v2, s[100:101]
	s_add_i32 m0, s16, 0x2000
	s_add_u32 s16, s28, 0x58080
	s_addc_u32 s17, s29, 0
	s_add_i32 s23, s50, s73
	global_load_lds_dwordx4 v168, s[100:101]
	s_mov_b32 m0, s23
	s_nop 0
	global_load_lds_dwordx4 v2, s[16:17]
	s_add_i32 m0, s23, 0x2000
	s_nop 0
	global_load_lds_dwordx4 v168, s[16:17]
	s_mov_b32 m0, s36
	s_nop 0
	s_add_u32 s100, vcc_lo, s24
	s_addc_u32 s101, vcc_hi, s25
	global_load_lds_dwordx4 v172, s[100:101]
	s_mov_b32 m0, s37
	s_nop 0
	global_load_lds_dwordx4 v170, s[100:101]
	s_waitcnt vmcnt(8) lgkmcnt(0)


	s_barrier
	v_mfma_f32_16x16x32_bf16 v[64:67], v[132:135], v[164:167], v[64:67]
	v_mfma_f32_16x16x32_bf16 v[60:63], v[140:143], v[164:167], v[60:63]
	v_mfma_f32_16x16x32_bf16 v[48:51], v[132:135], v[192:195], v[48:51]
	v_mfma_f32_16x16x32_bf16 v[44:47], v[140:143], v[192:195], v[44:47]
	v_mfma_f32_16x16x32_bf16 v[32:35], v[132:135], v[200:203], v[32:35]
	v_mfma_f32_16x16x32_bf16 v[28:31], v[140:143], v[200:203], v[28:31]
	v_mfma_f32_16x16x32_bf16 v[16:19], v[132:135], v[208:211], v[16:19]
	v_mfma_f32_16x16x32_bf16 v[12:15], v[140:143], v[208:211], v[12:15]
	v_mfma_f32_16x16x32_bf16 v[64:67], v[136:139], v[188:191], v[64:67]
	v_mfma_f32_16x16x32_bf16 v[60:63], v[144:147], v[188:191], v[60:63]
	v_mfma_f32_16x16x32_bf16 v[48:51], v[136:139], v[196:199], v[48:51]
	v_mfma_f32_16x16x32_bf16 v[44:47], v[144:147], v[196:199], v[44:47]
	v_mfma_f32_16x16x32_bf16 v[32:35], v[136:139], v[204:207], v[32:35]
	v_mfma_f32_16x16x32_bf16 v[28:31], v[144:147], v[204:207], v[28:31]
	v_mfma_f32_16x16x32_bf16 v[16:19], v[136:139], v[212:215], v[16:19]
	v_mfma_f32_16x16x32_bf16 v[12:15], v[144:147], v[212:215], v[12:15]
	v_mfma_f32_16x16x32_bf16 v[56:59], v[148:151], v[164:167], v[56:59]
	v_mfma_f32_16x16x32_bf16 v[52:55], v[156:159], v[164:167], v[52:55]
	v_mfma_f32_16x16x32_bf16 v[40:43], v[148:151], v[192:195], v[40:43]
	v_mfma_f32_16x16x32_bf16 v[36:39], v[156:159], v[192:195], v[36:39]
	v_mfma_f32_16x16x32_bf16 v[24:27], v[148:151], v[200:203], v[24:27]
	v_mfma_f32_16x16x32_bf16 v[20:23], v[156:159], v[200:203], v[20:23]
	v_mfma_f32_16x16x32_bf16 v[8:11], v[148:151], v[208:211], v[8:11]
	v_mfma_f32_16x16x32_bf16 v[4:7], v[156:159], v[208:211], v[4:7]
	v_mfma_f32_16x16x32_bf16 v[56:59], v[152:155], v[188:191], v[56:59]
	v_mfma_f32_16x16x32_bf16 v[52:55], v[160:163], v[188:191], v[52:55]
	v_mfma_f32_16x16x32_bf16 v[40:43], v[152:155], v[196:199], v[40:43]
	v_mfma_f32_16x16x32_bf16 v[36:39], v[160:163], v[196:199], v[36:39]
	v_mfma_f32_16x16x32_bf16 v[24:27], v[152:155], v[204:207], v[24:27]
	v_mfma_f32_16x16x32_bf16 v[20:23], v[160:163], v[204:207], v[20:23]
	v_mfma_f32_16x16x32_bf16 v[8:11], v[152:155], v[212:215], v[8:11]
	v_mfma_f32_16x16x32_bf16 v[4:7], v[160:163], v[212:215], v[4:7]
	s_barrier

	s_add_i32 s22, s22, 2
	s_add_u32 s31, s31, 0x100
	s_addc_u32 s33, s33, 0
	s_cmpk_gt_u32 s22, 0x55
	s_mov_b64 s[50:51], s[48:49]
	s_cbranch_scc0 .LBB0_366
	s_setprio 0
	v_readlane_b32 s16, v252, 12
	v_readlane_b32 s17, v252, 13

.LBB0_446:
	s_add_u32 s16, s44, 0xfff80080
	s_addc_u32 s17, s45, -1
	s_add_i32 s94, 0, 0x10000
	s_cmp_eq_u32 vcc_lo, 28
	s_cselect_b32 s47, s37, s17
	s_cselect_b32 s46, s88, s16
	s_cselect_b32 s29, s27, s96
	s_cselect_b32 s28, s89, s91
	s_add_i32 s95, 0, 0x14000
	ds_read_b128 v[132:135], v173
	ds_read_b128 v[136:139], v173 offset:1024
	ds_read_b128 v[140:143], v173 offset:2048
	ds_read_b128 v[144:147], v173 offset:3072
	ds_read_b128 v[148:151], v174
	ds_read_b128 v[164:167], v174 offset:1024
	ds_read_b128 v[168:171], v174 offset:2048
	ds_read_b128 v[184:187], v174 offset:3072
	s_add_i32 m0, s48, 0xc000
	ds_read_b128 v[188:191], v221
	ds_read_b128 v[192:195], v221 offset:1024
	ds_read_b128 v[196:199], v221 offset:2048
	ds_read_b128 v[200:203], v221 offset:3072
	ds_read_b128 v[204:207], v221 offset:4096
	ds_read_b128 v[208:211], v221 offset:5120
	ds_read_b128 v[212:215], v221 offset:6144
	ds_read_b128 v[222:225], v221 offset:7168
	global_load_lds_dwordx4 v160, s[44:45]
	s_add_i32 m0, s48, 0xe000
	s_nop 0
	global_load_lds_dwordx4 v162, s[44:45]
	s_waitcnt vmcnt(8) lgkmcnt(0)


	s_barrier
	v_mfma_f32_16x16x32_bf16 v[128:131], v[132:135], v[188:191], v[128:131]
	v_mfma_f32_16x16x32_bf16 v[124:127], v[140:143], v[188:191], v[124:127]
	v_mfma_f32_16x16x32_bf16 v[112:115], v[132:135], v[196:199], v[112:115]
	v_mfma_f32_16x16x32_bf16 v[108:111], v[140:143], v[196:199], v[108:111]
	v_mfma_f32_16x16x32_bf16 v[96:99], v[132:135], v[204:207], v[96:99]
	v_mfma_f32_16x16x32_bf16 v[92:95], v[140:143], v[204:207], v[92:95]
	v_mfma_f32_16x16x32_bf16 v[80:83], v[132:135], v[212:215], v[80:83]
	v_mfma_f32_16x16x32_bf16 v[76:79], v[140:143], v[212:215], v[76:79]
	v_mfma_f32_16x16x32_bf16 v[128:131], v[136:139], v[192:195], v[128:131]
	v_mfma_f32_16x16x32_bf16 v[124:127], v[144:147], v[192:195], v[124:127]
	v_mfma_f32_16x16x32_bf16 v[112:115], v[136:139], v[200:203], v[112:115]
	v_mfma_f32_16x16x32_bf16 v[108:111], v[144:147], v[200:203], v[108:111]
	v_mfma_f32_16x16x32_bf16 v[96:99], v[136:139], v[208:211], v[96:99]
	v_mfma_f32_16x16x32_bf16 v[92:95], v[144:147], v[208:211], v[92:95]
	v_mfma_f32_16x16x32_bf16 v[80:83], v[136:139], v[222:225], v[80:83]
	v_mfma_f32_16x16x32_bf16 v[76:79], v[144:147], v[222:225], v[76:79]
	v_mfma_f32_16x16x32_bf16 v[120:123], v[148:151], v[188:191], v[120:123]
	v_mfma_f32_16x16x32_bf16 v[116:119], v[168:171], v[188:191], v[116:119]
	v_mfma_f32_16x16x32_bf16 v[104:107], v[148:151], v[196:199], v[104:107]
	v_mfma_f32_16x16x32_bf16 v[100:103], v[168:171], v[196:199], v[100:103]
	v_mfma_f32_16x16x32_bf16 v[88:91], v[148:151], v[204:207], v[88:91]
	v_mfma_f32_16x16x32_bf16 v[84:87], v[168:171], v[204:207], v[84:87]
	v_mfma_f32_16x16x32_bf16 v[72:75], v[148:151], v[212:215], v[72:75]
	v_mfma_f32_16x16x32_bf16 v[68:71], v[168:171], v[212:215], v[68:71]
	v_mfma_f32_16x16x32_bf16 v[120:123], v[164:167], v[192:195], v[120:123]
	v_mfma_f32_16x16x32_bf16 v[116:119], v[184:187], v[192:195], v[116:119]
	v_mfma_f32_16x16x32_bf16 v[104:107], v[164:167], v[200:203], v[104:107]
	v_mfma_f32_16x16x32_bf16 v[100:103], v[184:187], v[200:203], v[100:103]
	v_mfma_f32_16x16x32_bf16 v[88:91], v[164:167], v[208:211], v[88:91]
	v_mfma_f32_16x16x32_bf16 v[84:87], v[184:187], v[208:211], v[84:87]
	v_mfma_f32_16x16x32_bf16 v[72:75], v[164:167], v[222:225], v[72:75]
	v_mfma_f32_16x16x32_bf16 v[68:71], v[184:187], v[222:225], v[68:71]
	s_barrier

	s_add_i32 s16, s94, s33
	s_mov_b32 m0, s16
	ds_read_b128 v[188:191], v221 offset:16384
	ds_read_b128 v[192:195], v221 offset:17408
	ds_read_b128 v[196:199], v221 offset:18432
	ds_read_b128 v[200:203], v221 offset:19456
	ds_read_b128 v[204:207], v221 offset:20480
	ds_read_b128 v[208:211], v221 offset:21504
	ds_read_b128 v[212:215], v221 offset:22528
	ds_read_b128 v[222:225], v221 offset:23552
	global_load_lds_dwordx4 v2, s[28:29]
	s_add_i32 m0, s16, 0x2000
	s_add_u32 s16, s28, 0x80000
	s_addc_u32 s17, s29, 0
	s_add_i32 s94, s95, s33
	global_load_lds_dwordx4 v152, s[28:29]
	s_mov_b32 m0, s94
	s_nop 0
	global_load_lds_dwordx4 v2, s[16:17]
	s_add_i32 m0, s94, 0x2000
	s_nop 0
	global_load_lds_dwordx4 v152, s[16:17]
	s_mov_b32 m0, s48
	s_nop 0
	global_load_lds_dwordx4 v156, s[46:47]
	s_mov_b32 m0, s49
	s_nop 0
	global_load_lds_dwordx4 v154, s[46:47]
	s_waitcnt vmcnt(8) lgkmcnt(0)


	s_barrier
	v_mfma_f32_16x16x32_bf16 v[64:67], v[132:135], v[188:191], v[64:67]
	v_mfma_f32_16x16x32_bf16 v[60:63], v[140:143], v[188:191], v[60:63]
	v_mfma_f32_16x16x32_bf16 v[48:51], v[132:135], v[196:199], v[48:51]
	v_mfma_f32_16x16x32_bf16 v[44:47], v[140:143], v[196:199], v[44:47]
	v_mfma_f32_16x16x32_bf16 v[32:35], v[132:135], v[204:207], v[32:35]
	v_mfma_f32_16x16x32_bf16 v[28:31], v[140:143], v[204:207], v[28:31]
	v_mfma_f32_16x16x32_bf16 v[16:19], v[132:135], v[212:215], v[16:19]
	v_mfma_f32_16x16x32_bf16 v[12:15], v[140:143], v[212:215], v[12:15]
	v_mfma_f32_16x16x32_bf16 v[64:67], v[136:139], v[192:195], v[64:67]
	v_mfma_f32_16x16x32_bf16 v[60:63], v[144:147], v[192:195], v[60:63]
	v_mfma_f32_16x16x32_bf16 v[48:51], v[136:139], v[200:203], v[48:51]
	v_mfma_f32_16x16x32_bf16 v[44:47], v[144:147], v[200:203], v[44:47]
	v_mfma_f32_16x16x32_bf16 v[32:35], v[136:139], v[208:211], v[32:35]
	v_mfma_f32_16x16x32_bf16 v[28:31], v[144:147], v[208:211], v[28:31]
	v_mfma_f32_16x16x32_bf16 v[16:19], v[136:139], v[222:225], v[16:19]
	v_mfma_f32_16x16x32_bf16 v[12:15], v[144:147], v[222:225], v[12:15]
	v_mfma_f32_16x16x32_bf16 v[56:59], v[148:151], v[188:191], v[56:59]
	v_mfma_f32_16x16x32_bf16 v[52:55], v[168:171], v[188:191], v[52:55]
	v_mfma_f32_16x16x32_bf16 v[40:43], v[148:151], v[196:199], v[40:43]
	v_mfma_f32_16x16x32_bf16 v[36:39], v[168:171], v[196:199], v[36:39]
	v_mfma_f32_16x16x32_bf16 v[24:27], v[148:151], v[204:207], v[24:27]
	v_mfma_f32_16x16x32_bf16 v[20:23], v[168:171], v[204:207], v[20:23]
	v_mfma_f32_16x16x32_bf16 v[8:11], v[148:151], v[212:215], v[8:11]
	v_mfma_f32_16x16x32_bf16 v[4:7], v[168:171], v[212:215], v[4:7]
	v_mfma_f32_16x16x32_bf16 v[56:59], v[164:167], v[192:195], v[56:59]
	v_mfma_f32_16x16x32_bf16 v[52:55], v[184:187], v[192:195], v[52:55]
	v_mfma_f32_16x16x32_bf16 v[40:43], v[164:167], v[200:203], v[40:43]
	v_mfma_f32_16x16x32_bf16 v[36:39], v[184:187], v[200:203], v[36:39]
	v_mfma_f32_16x16x32_bf16 v[24:27], v[164:167], v[208:211], v[24:27]
	v_mfma_f32_16x16x32_bf16 v[20:23], v[184:187], v[208:211], v[20:23]
	v_mfma_f32_16x16x32_bf16 v[8:11], v[164:167], v[222:225], v[8:11]
	v_mfma_f32_16x16x32_bf16 v[4:7], v[184:187], v[222:225], v[4:7]
	s_barrier

	s_add_i32 s94, 0, 0x18000
	s_add_i32 s95, 0, 0x1c000
	ds_read_b128 v[132:135], v175
	ds_read_b128 v[136:139], v175 offset:1024
	ds_read_b128 v[140:143], v175 offset:2048
	ds_read_b128 v[144:147], v175 offset:3072
	ds_read_b128 v[148:151], v182
	ds_read_b128 v[164:167], v182 offset:1024
	ds_read_b128 v[168:171], v182 offset:2048
	ds_read_b128 v[184:187], v182 offset:3072
	s_add_u32 s16, s46, 0x80000
	s_addc_u32 s17, s47, 0
	s_mov_b32 m0, s50
	ds_read_b128 v[188:191], v221 offset:32768
	ds_read_b128 v[192:195], v221 offset:33792
	ds_read_b128 v[196:199], v221 offset:34816
	ds_read_b128 v[200:203], v221 offset:35840
	ds_read_b128 v[204:207], v221 offset:36864
	ds_read_b128 v[208:211], v221 offset:37888
	ds_read_b128 v[212:215], v221 offset:38912
	ds_read_b128 v[222:225], v221 offset:39936
	global_load_lds_dwordx4 v156, s[16:17]
	s_mov_b32 m0, s51
	s_nop 0
	global_load_lds_dwordx4 v154, s[16:17]
	s_waitcnt vmcnt(8) lgkmcnt(0)


	s_barrier
	v_mfma_f32_16x16x32_bf16 v[128:131], v[132:135], v[188:191], v[128:131]
	v_mfma_f32_16x16x32_bf16 v[124:127], v[140:143], v[188:191], v[124:127]
	v_mfma_f32_16x16x32_bf16 v[112:115], v[132:135], v[196:199], v[112:115]
	v_mfma_f32_16x16x32_bf16 v[108:111], v[140:143], v[196:199], v[108:111]
	v_mfma_f32_16x16x32_bf16 v[96:99], v[132:135], v[204:207], v[96:99]
	v_mfma_f32_16x16x32_bf16 v[92:95], v[140:143], v[204:207], v[92:95]
	v_mfma_f32_16x16x32_bf16 v[80:83], v[132:135], v[212:215], v[80:83]
	v_mfma_f32_16x16x32_bf16 v[76:79], v[140:143], v[212:215], v[76:79]
	v_mfma_f32_16x16x32_bf16 v[128:131], v[136:139], v[192:195], v[128:131]
	v_mfma_f32_16x16x32_bf16 v[124:127], v[144:147], v[192:195], v[124:127]
	v_mfma_f32_16x16x32_bf16 v[112:115], v[136:139], v[200:203], v[112:115]
	v_mfma_f32_16x16x32_bf16 v[108:111], v[144:147], v[200:203], v[108:111]
	v_mfma_f32_16x16x32_bf16 v[96:99], v[136:139], v[208:211], v[96:99]
	v_mfma_f32_16x16x32_bf16 v[92:95], v[144:147], v[208:211], v[92:95]
	v_mfma_f32_16x16x32_bf16 v[80:83], v[136:139], v[222:225], v[80:83]
	v_mfma_f32_16x16x32_bf16 v[76:79], v[144:147], v[222:225], v[76:79]
	v_mfma_f32_16x16x32_bf16 v[120:123], v[148:151], v[188:191], v[120:123]
	v_mfma_f32_16x16x32_bf16 v[116:119], v[168:171], v[188:191], v[116:119]
	v_mfma_f32_16x16x32_bf16 v[104:107], v[148:151], v[196:199], v[104:107]
	v_mfma_f32_16x16x32_bf16 v[100:103], v[168:171], v[196:199], v[100:103]
	v_mfma_f32_16x16x32_bf16 v[88:91], v[148:151], v[204:207], v[88:91]
	v_mfma_f32_16x16x32_bf16 v[84:87], v[168:171], v[204:207], v[84:87]
	v_mfma_f32_16x16x32_bf16 v[72:75], v[148:151], v[212:215], v[72:75]
	v_mfma_f32_16x16x32_bf16 v[68:71], v[168:171], v[212:215], v[68:71]
	v_mfma_f32_16x16x32_bf16 v[120:123], v[164:167], v[192:195], v[120:123]
	v_mfma_f32_16x16x32_bf16 v[116:119], v[184:187], v[192:195], v[116:119]
	v_mfma_f32_16x16x32_bf16 v[104:107], v[164:167], v[200:203], v[104:107]
	v_mfma_f32_16x16x32_bf16 v[100:103], v[184:187], v[200:203], v[100:103]
	v_mfma_f32_16x16x32_bf16 v[88:91], v[164:167], v[208:211], v[88:91]
	v_mfma_f32_16x16x32_bf16 v[84:87], v[184:187], v[208:211], v[84:87]
	v_mfma_f32_16x16x32_bf16 v[72:75], v[164:167], v[222:225], v[72:75]
	v_mfma_f32_16x16x32_bf16 v[68:71], v[184:187], v[222:225], v[68:71]
	s_barrier

	s_add_i32 s16, s94, s33
	s_mov_b32 m0, s16
	ds_read_b128 v[188:191], v221 offset:49152
	ds_read_b128 v[192:195], v221 offset:50176
	ds_read_b128 v[196:199], v221 offset:51200
	ds_read_b128 v[200:203], v221 offset:52224
	ds_read_b128 v[204:207], v221 offset:53248
	ds_read_b128 v[208:211], v221 offset:54272
	ds_read_b128 v[212:215], v221 offset:55296
	ds_read_b128 v[222:225], v221 offset:56320
	s_add_u32 s100, s28, s24
	s_addc_u32 s101, s29, s25
	global_load_lds_dwordx4 v2, s[100:101]
	s_add_i32 m0, s16, 0x2000
	s_add_u32 s16, s28, 0x80080
	s_addc_u32 s17, s29, 0
	s_add_i32 s28, s95, s33
	global_load_lds_dwordx4 v152, s[100:101]
	s_mov_b32 m0, s28
	s_nop 0
	global_load_lds_dwordx4 v2, s[16:17]
	s_add_i32 m0, s28, 0x2000
	s_nop 0
	global_load_lds_dwordx4 v152, s[16:17]
	s_mov_b32 m0, s72
	s_nop 0
	s_add_u32 s100, s46, s24
	s_addc_u32 s101, s47, s25
	global_load_lds_dwordx4 v156, s[100:101]
	s_mov_b32 m0, s73
	s_nop 0
	global_load_lds_dwordx4 v154, s[100:101]
	s_waitcnt vmcnt(8) lgkmcnt(0)


	s_barrier
	v_mfma_f32_16x16x32_bf16 v[64:67], v[132:135], v[188:191], v[64:67]
	v_mfma_f32_16x16x32_bf16 v[60:63], v[140:143], v[188:191], v[60:63]
	v_mfma_f32_16x16x32_bf16 v[48:51], v[132:135], v[196:199], v[48:51]
	v_mfma_f32_16x16x32_bf16 v[44:47], v[140:143], v[196:199], v[44:47]
	v_mfma_f32_16x16x32_bf16 v[32:35], v[132:135], v[204:207], v[32:35]
	v_mfma_f32_16x16x32_bf16 v[28:31], v[140:143], v[204:207], v[28:31]
	v_mfma_f32_16x16x32_bf16 v[16:19], v[132:135], v[212:215], v[16:19]
	v_mfma_f32_16x16x32_bf16 v[12:15], v[140:143], v[212:215], v[12:15]
	v_mfma_f32_16x16x32_bf16 v[64:67], v[136:139], v[192:195], v[64:67]
	v_mfma_f32_16x16x32_bf16 v[60:63], v[144:147], v[192:195], v[60:63]
	v_mfma_f32_16x16x32_bf16 v[48:51], v[136:139], v[200:203], v[48:51]
	v_mfma_f32_16x16x32_bf16 v[44:47], v[144:147], v[200:203], v[44:47]
	v_mfma_f32_16x16x32_bf16 v[32:35], v[136:139], v[208:211], v[32:35]
	v_mfma_f32_16x16x32_bf16 v[28:31], v[144:147], v[208:211], v[28:31]
	v_mfma_f32_16x16x32_bf16 v[16:19], v[136:139], v[222:225], v[16:19]
	v_mfma_f32_16x16x32_bf16 v[12:15], v[144:147], v[222:225], v[12:15]
	v_mfma_f32_16x16x32_bf16 v[56:59], v[148:151], v[188:191], v[56:59]
	v_mfma_f32_16x16x32_bf16 v[52:55], v[168:171], v[188:191], v[52:55]
	v_mfma_f32_16x16x32_bf16 v[40:43], v[148:151], v[196:199], v[40:43]
	v_mfma_f32_16x16x32_bf16 v[36:39], v[168:171], v[196:199], v[36:39]
	v_mfma_f32_16x16x32_bf16 v[24:27], v[148:151], v[204:207], v[24:27]
	v_mfma_f32_16x16x32_bf16 v[20:23], v[168:171], v[204:207], v[20:23]
	v_mfma_f32_16x16x32_bf16 v[8:11], v[148:151], v[212:215], v[8:11]
	v_mfma_f32_16x16x32_bf16 v[4:7], v[168:171], v[212:215], v[4:7]
	v_mfma_f32_16x16x32_bf16 v[56:59], v[164:167], v[192:195], v[56:59]
	v_mfma_f32_16x16x32_bf16 v[52:55], v[184:187], v[192:195], v[52:55]
	v_mfma_f32_16x16x32_bf16 v[40:43], v[164:167], v[200:203], v[40:43]
	v_mfma_f32_16x16x32_bf16 v[36:39], v[184:187], v[200:203], v[36:39]
	v_mfma_f32_16x16x32_bf16 v[24:27], v[164:167], v[208:211], v[24:27]
	v_mfma_f32_16x16x32_bf16 v[20:23], v[184:187], v[208:211], v[20:23]
	v_mfma_f32_16x16x32_bf16 v[8:11], v[164:167], v[222:225], v[8:11]
	v_mfma_f32_16x16x32_bf16 v[4:7], v[184:187], v[222:225], v[4:7]
	s_barrier

	s_add_i32 vcc_lo, vcc_lo, 2
	s_add_u32 s44, s44, 0x100
	s_addc_u32 s45, s45, 0
	s_add_u32 s91, s91, 0x100
	s_addc_u32 s96, s96, 0
	s_cmp_gt_u32 vcc_lo, 29
	s_cbranch_scc0 .LBB0_446
	s_setprio 0
	v_mov_b32_e32 v250, 0xc2000000
	v_mov_b32_e32 v1, 0xbfb8aa3b
	v_mov_b64_e32 v[238:239], v[236:237]

.LBB0_790:
	s_add_u32 s11, vcc_lo, 0xfff80080
	s_addc_u32 s16, vcc_hi, -1
	s_add_i32 s17, 0, 0x10000
	s_cmp_eq_u32 s10, 28
	s_cselect_b32 s73, s19, s16
	s_cselect_b32 s72, s31, s11
	s_cselect_b32 s29, s23, s49
	s_cselect_b32 s28, s33, s48
	s_add_i32 s11, 0, 0x14000
	ds_read_b128 v[132:135], v174
	ds_read_b128 v[136:139], v174 offset:1024
	ds_read_b128 v[140:143], v174 offset:2048
	ds_read_b128 v[144:147], v174 offset:3072
	ds_read_b128 v[148:151], v175
	ds_read_b128 v[152:155], v175 offset:1024
	ds_read_b128 v[156:159], v175 offset:2048
	ds_read_b128 v[160:163], v175 offset:3072
	s_add_i32 m0, s77, 0xc000
	ds_read_b128 v[164:167], v246
	ds_read_b128 v[188:191], v246 offset:1024
	ds_read_b128 v[192:195], v246 offset:2048
	ds_read_b128 v[196:199], v246 offset:3072
	ds_read_b128 v[200:203], v246 offset:4096
	ds_read_b128 v[204:207], v246 offset:5120
	ds_read_b128 v[208:211], v246 offset:6144
	ds_read_b128 v[212:215], v246 offset:7168
	global_load_lds_dwordx4 v184, vcc
	s_add_i32 m0, s77, 0xe000
	s_nop 0
	global_load_lds_dwordx4 v186, vcc
	s_waitcnt vmcnt(8) lgkmcnt(0)


	s_barrier
	v_mfma_f32_16x16x32_bf16 v[128:131], v[132:135], v[164:167], v[128:131]
	v_mfma_f32_16x16x32_bf16 v[124:127], v[140:143], v[164:167], v[124:127]
	v_mfma_f32_16x16x32_bf16 v[112:115], v[132:135], v[192:195], v[112:115]
	v_mfma_f32_16x16x32_bf16 v[108:111], v[140:143], v[192:195], v[108:111]
	v_mfma_f32_16x16x32_bf16 v[96:99], v[132:135], v[200:203], v[96:99]
	v_mfma_f32_16x16x32_bf16 v[92:95], v[140:143], v[200:203], v[92:95]
	v_mfma_f32_16x16x32_bf16 v[80:83], v[132:135], v[208:211], v[80:83]
	v_mfma_f32_16x16x32_bf16 v[76:79], v[140:143], v[208:211], v[76:79]
	v_mfma_f32_16x16x32_bf16 v[128:131], v[136:139], v[188:191], v[128:131]
	v_mfma_f32_16x16x32_bf16 v[124:127], v[144:147], v[188:191], v[124:127]
	v_mfma_f32_16x16x32_bf16 v[112:115], v[136:139], v[196:199], v[112:115]
	v_mfma_f32_16x16x32_bf16 v[108:111], v[144:147], v[196:199], v[108:111]
	v_mfma_f32_16x16x32_bf16 v[96:99], v[136:139], v[204:207], v[96:99]
	v_mfma_f32_16x16x32_bf16 v[92:95], v[144:147], v[204:207], v[92:95]
	v_mfma_f32_16x16x32_bf16 v[80:83], v[136:139], v[212:215], v[80:83]
	v_mfma_f32_16x16x32_bf16 v[76:79], v[144:147], v[212:215], v[76:79]
	v_mfma_f32_16x16x32_bf16 v[120:123], v[148:151], v[164:167], v[120:123]
	v_mfma_f32_16x16x32_bf16 v[116:119], v[156:159], v[164:167], v[116:119]
	v_mfma_f32_16x16x32_bf16 v[104:107], v[148:151], v[192:195], v[104:107]
	v_mfma_f32_16x16x32_bf16 v[100:103], v[156:159], v[192:195], v[100:103]
	v_mfma_f32_16x16x32_bf16 v[88:91], v[148:151], v[200:203], v[88:91]
	v_mfma_f32_16x16x32_bf16 v[84:87], v[156:159], v[200:203], v[84:87]
	v_mfma_f32_16x16x32_bf16 v[72:75], v[148:151], v[208:211], v[72:75]
	v_mfma_f32_16x16x32_bf16 v[68:71], v[156:159], v[208:211], v[68:71]
	v_mfma_f32_16x16x32_bf16 v[120:123], v[152:155], v[188:191], v[120:123]
	v_mfma_f32_16x16x32_bf16 v[116:119], v[160:163], v[188:191], v[116:119]
	v_mfma_f32_16x16x32_bf16 v[104:107], v[152:155], v[196:199], v[104:107]
	v_mfma_f32_16x16x32_bf16 v[100:103], v[160:163], v[196:199], v[100:103]
	v_mfma_f32_16x16x32_bf16 v[88:91], v[152:155], v[204:207], v[88:91]
	v_mfma_f32_16x16x32_bf16 v[84:87], v[160:163], v[204:207], v[84:87]
	v_mfma_f32_16x16x32_bf16 v[72:75], v[152:155], v[212:215], v[72:75]
	v_mfma_f32_16x16x32_bf16 v[68:71], v[160:163], v[212:215], v[68:71]
	s_barrier

	s_add_i32 s16, s17, s74
	s_mov_b32 m0, s16
	ds_read_b128 v[164:167], v246 offset:16384
	ds_read_b128 v[188:191], v246 offset:17408
	ds_read_b128 v[192:195], v246 offset:18432
	ds_read_b128 v[196:199], v246 offset:19456
	ds_read_b128 v[200:203], v246 offset:20480
	ds_read_b128 v[204:207], v246 offset:21504
	ds_read_b128 v[208:211], v246 offset:22528
	ds_read_b128 v[212:215], v246 offset:23552
	global_load_lds_dwordx4 v2, s[28:29]
	s_add_i32 m0, s16, 0x2000
	s_add_u32 s16, s28, 0x20000
	s_addc_u32 s17, s29, 0
	s_add_i32 s11, s11, s74
	global_load_lds_dwordx4 v168, s[28:29]
	s_mov_b32 m0, s11
	s_nop 0
	global_load_lds_dwordx4 v2, s[16:17]
	s_add_i32 m0, s11, 0x2000
	s_nop 0
	global_load_lds_dwordx4 v168, s[16:17]
	s_mov_b32 m0, s77
	s_nop 0
	global_load_lds_dwordx4 v172, s[72:73]
	s_mov_b32 m0, s78
	s_nop 0
	global_load_lds_dwordx4 v170, s[72:73]
	s_waitcnt vmcnt(8) lgkmcnt(0)


	s_barrier
	v_mfma_f32_16x16x32_bf16 v[64:67], v[132:135], v[164:167], v[64:67]
	v_mfma_f32_16x16x32_bf16 v[60:63], v[140:143], v[164:167], v[60:63]
	v_mfma_f32_16x16x32_bf16 v[48:51], v[132:135], v[192:195], v[48:51]
	v_mfma_f32_16x16x32_bf16 v[44:47], v[140:143], v[192:195], v[44:47]
	v_mfma_f32_16x16x32_bf16 v[32:35], v[132:135], v[200:203], v[32:35]
	v_mfma_f32_16x16x32_bf16 v[28:31], v[140:143], v[200:203], v[28:31]
	v_mfma_f32_16x16x32_bf16 v[16:19], v[132:135], v[208:211], v[16:19]
	v_mfma_f32_16x16x32_bf16 v[12:15], v[140:143], v[208:211], v[12:15]
	v_mfma_f32_16x16x32_bf16 v[64:67], v[136:139], v[188:191], v[64:67]
	v_mfma_f32_16x16x32_bf16 v[60:63], v[144:147], v[188:191], v[60:63]
	v_mfma_f32_16x16x32_bf16 v[48:51], v[136:139], v[196:199], v[48:51]
	v_mfma_f32_16x16x32_bf16 v[44:47], v[144:147], v[196:199], v[44:47]
	v_mfma_f32_16x16x32_bf16 v[32:35], v[136:139], v[204:207], v[32:35]
	v_mfma_f32_16x16x32_bf16 v[28:31], v[144:147], v[204:207], v[28:31]
	v_mfma_f32_16x16x32_bf16 v[16:19], v[136:139], v[212:215], v[16:19]
	v_mfma_f32_16x16x32_bf16 v[12:15], v[144:147], v[212:215], v[12:15]
	v_mfma_f32_16x16x32_bf16 v[56:59], v[148:151], v[164:167], v[56:59]
	v_mfma_f32_16x16x32_bf16 v[52:55], v[156:159], v[164:167], v[52:55]
	v_mfma_f32_16x16x32_bf16 v[40:43], v[148:151], v[192:195], v[40:43]
	v_mfma_f32_16x16x32_bf16 v[36:39], v[156:159], v[192:195], v[36:39]
	v_mfma_f32_16x16x32_bf16 v[24:27], v[148:151], v[200:203], v[24:27]
	v_mfma_f32_16x16x32_bf16 v[20:23], v[156:159], v[200:203], v[20:23]
	v_mfma_f32_16x16x32_bf16 v[8:11], v[148:151], v[208:211], v[8:11]
	v_mfma_f32_16x16x32_bf16 v[4:7], v[156:159], v[208:211], v[4:7]
	v_mfma_f32_16x16x32_bf16 v[56:59], v[152:155], v[188:191], v[56:59]
	v_mfma_f32_16x16x32_bf16 v[52:55], v[160:163], v[188:191], v[52:55]
	v_mfma_f32_16x16x32_bf16 v[40:43], v[152:155], v[196:199], v[40:43]
	v_mfma_f32_16x16x32_bf16 v[36:39], v[160:163], v[196:199], v[36:39]
	v_mfma_f32_16x16x32_bf16 v[24:27], v[152:155], v[204:207], v[24:27]
	v_mfma_f32_16x16x32_bf16 v[20:23], v[160:163], v[204:207], v[20:23]
	v_mfma_f32_16x16x32_bf16 v[8:11], v[152:155], v[212:215], v[8:11]
	v_mfma_f32_16x16x32_bf16 v[4:7], v[160:163], v[212:215], v[4:7]
	s_barrier

	s_add_i32 s11, 0, 0x18000
	s_add_i32 s94, 0, 0x1c000
	ds_read_b128 v[132:135], v176
	ds_read_b128 v[136:139], v176 offset:1024
	ds_read_b128 v[140:143], v176 offset:2048
	ds_read_b128 v[144:147], v176 offset:3072
	ds_read_b128 v[148:151], v177
	ds_read_b128 v[152:155], v177 offset:1024
	ds_read_b128 v[156:159], v177 offset:2048
	ds_read_b128 v[160:163], v177 offset:3072
	s_add_u32 s16, s72, 0x80000
	s_addc_u32 s17, s73, 0
	s_mov_b32 m0, s95
	ds_read_b128 v[164:167], v246 offset:32768
	ds_read_b128 v[188:191], v246 offset:33792
	ds_read_b128 v[192:195], v246 offset:34816
	ds_read_b128 v[196:199], v246 offset:35840
	ds_read_b128 v[200:203], v246 offset:36864
	ds_read_b128 v[204:207], v246 offset:37888
	ds_read_b128 v[208:211], v246 offset:38912
	ds_read_b128 v[212:215], v246 offset:39936
	global_load_lds_dwordx4 v172, s[16:17]
	s_mov_b32 m0, s68
	s_nop 0
	global_load_lds_dwordx4 v170, s[16:17]
	s_waitcnt vmcnt(8) lgkmcnt(0)


	s_barrier
	v_mfma_f32_16x16x32_bf16 v[128:131], v[132:135], v[164:167], v[128:131]
	v_mfma_f32_16x16x32_bf16 v[124:127], v[140:143], v[164:167], v[124:127]
	v_mfma_f32_16x16x32_bf16 v[112:115], v[132:135], v[192:195], v[112:115]
	v_mfma_f32_16x16x32_bf16 v[108:111], v[140:143], v[192:195], v[108:111]
	v_mfma_f32_16x16x32_bf16 v[96:99], v[132:135], v[200:203], v[96:99]
	v_mfma_f32_16x16x32_bf16 v[92:95], v[140:143], v[200:203], v[92:95]
	v_mfma_f32_16x16x32_bf16 v[80:83], v[132:135], v[208:211], v[80:83]
	v_mfma_f32_16x16x32_bf16 v[76:79], v[140:143], v[208:211], v[76:79]
	v_mfma_f32_16x16x32_bf16 v[128:131], v[136:139], v[188:191], v[128:131]
	v_mfma_f32_16x16x32_bf16 v[124:127], v[144:147], v[188:191], v[124:127]
	v_mfma_f32_16x16x32_bf16 v[112:115], v[136:139], v[196:199], v[112:115]
	v_mfma_f32_16x16x32_bf16 v[108:111], v[144:147], v[196:199], v[108:111]
	v_mfma_f32_16x16x32_bf16 v[96:99], v[136:139], v[204:207], v[96:99]
	v_mfma_f32_16x16x32_bf16 v[92:95], v[144:147], v[204:207], v[92:95]
	v_mfma_f32_16x16x32_bf16 v[80:83], v[136:139], v[212:215], v[80:83]
	v_mfma_f32_16x16x32_bf16 v[76:79], v[144:147], v[212:215], v[76:79]
	v_mfma_f32_16x16x32_bf16 v[120:123], v[148:151], v[164:167], v[120:123]
	v_mfma_f32_16x16x32_bf16 v[116:119], v[156:159], v[164:167], v[116:119]
	v_mfma_f32_16x16x32_bf16 v[104:107], v[148:151], v[192:195], v[104:107]
	v_mfma_f32_16x16x32_bf16 v[100:103], v[156:159], v[192:195], v[100:103]
	v_mfma_f32_16x16x32_bf16 v[88:91], v[148:151], v[200:203], v[88:91]
	v_mfma_f32_16x16x32_bf16 v[84:87], v[156:159], v[200:203], v[84:87]
	v_mfma_f32_16x16x32_bf16 v[72:75], v[148:151], v[208:211], v[72:75]
	v_mfma_f32_16x16x32_bf16 v[68:71], v[156:159], v[208:211], v[68:71]
	v_mfma_f32_16x16x32_bf16 v[120:123], v[152:155], v[188:191], v[120:123]
	v_mfma_f32_16x16x32_bf16 v[116:119], v[160:163], v[188:191], v[116:119]
	v_mfma_f32_16x16x32_bf16 v[104:107], v[152:155], v[196:199], v[104:107]
	v_mfma_f32_16x16x32_bf16 v[100:103], v[160:163], v[196:199], v[100:103]
	v_mfma_f32_16x16x32_bf16 v[88:91], v[152:155], v[204:207], v[88:91]
	v_mfma_f32_16x16x32_bf16 v[84:87], v[160:163], v[204:207], v[84:87]
	v_mfma_f32_16x16x32_bf16 v[72:75], v[152:155], v[212:215], v[72:75]
	v_mfma_f32_16x16x32_bf16 v[68:71], v[160:163], v[212:215], v[68:71]
	s_barrier

	s_add_i32 s11, s11, s74
	s_mov_b32 m0, s11
	ds_read_b128 v[164:167], v246 offset:49152
	ds_read_b128 v[188:191], v246 offset:50176
	ds_read_b128 v[192:195], v246 offset:51200
	ds_read_b128 v[196:199], v246 offset:52224
	ds_read_b128 v[200:203], v246 offset:53248
	ds_read_b128 v[204:207], v246 offset:54272
	ds_read_b128 v[208:211], v246 offset:55296
	ds_read_b128 v[212:215], v246 offset:56320
	s_add_u32 s100, s28, s24
	s_addc_u32 s101, s29, s25
	global_load_lds_dwordx4 v2, s[100:101]
	s_add_i32 m0, s11, 0x2000
	s_add_u32 s16, s28, 0x20080
	s_addc_u32 s17, s29, 0
	s_add_i32 s11, s94, s74
	global_load_lds_dwordx4 v168, s[100:101]
	s_mov_b32 m0, s11
	s_nop 0
	global_load_lds_dwordx4 v2, s[16:17]
	s_add_i32 m0, s11, 0x2000
	s_nop 0
	global_load_lds_dwordx4 v168, s[16:17]
	s_mov_b32 m0, s96
	s_nop 0
	s_add_u32 s100, s72, s24
	s_addc_u32 s101, s73, s25
	global_load_lds_dwordx4 v172, s[100:101]
	s_mov_b32 m0, s3
	s_nop 0
	global_load_lds_dwordx4 v170, s[100:101]
	s_waitcnt vmcnt(8) lgkmcnt(0)


	s_barrier
	v_mfma_f32_16x16x32_bf16 v[64:67], v[132:135], v[164:167], v[64:67]
	v_mfma_f32_16x16x32_bf16 v[60:63], v[140:143], v[164:167], v[60:63]
	v_mfma_f32_16x16x32_bf16 v[48:51], v[132:135], v[192:195], v[48:51]
	v_mfma_f32_16x16x32_bf16 v[44:47], v[140:143], v[192:195], v[44:47]
	v_mfma_f32_16x16x32_bf16 v[32:35], v[132:135], v[200:203], v[32:35]
	v_mfma_f32_16x16x32_bf16 v[28:31], v[140:143], v[200:203], v[28:31]
	v_mfma_f32_16x16x32_bf16 v[16:19], v[132:135], v[208:211], v[16:19]
	v_mfma_f32_16x16x32_bf16 v[12:15], v[140:143], v[208:211], v[12:15]
	v_mfma_f32_16x16x32_bf16 v[64:67], v[136:139], v[188:191], v[64:67]
	v_mfma_f32_16x16x32_bf16 v[60:63], v[144:147], v[188:191], v[60:63]
	v_mfma_f32_16x16x32_bf16 v[48:51], v[136:139], v[196:199], v[48:51]
	v_mfma_f32_16x16x32_bf16 v[44:47], v[144:147], v[196:199], v[44:47]
	v_mfma_f32_16x16x32_bf16 v[32:35], v[136:139], v[204:207], v[32:35]
	v_mfma_f32_16x16x32_bf16 v[28:31], v[144:147], v[204:207], v[28:31]
	v_mfma_f32_16x16x32_bf16 v[16:19], v[136:139], v[212:215], v[16:19]
	v_mfma_f32_16x16x32_bf16 v[12:15], v[144:147], v[212:215], v[12:15]
	v_mfma_f32_16x16x32_bf16 v[56:59], v[148:151], v[164:167], v[56:59]
	v_mfma_f32_16x16x32_bf16 v[52:55], v[156:159], v[164:167], v[52:55]
	v_mfma_f32_16x16x32_bf16 v[40:43], v[148:151], v[192:195], v[40:43]
	v_mfma_f32_16x16x32_bf16 v[36:39], v[156:159], v[192:195], v[36:39]
	v_mfma_f32_16x16x32_bf16 v[24:27], v[148:151], v[200:203], v[24:27]
	v_mfma_f32_16x16x32_bf16 v[20:23], v[156:159], v[200:203], v[20:23]
	v_mfma_f32_16x16x32_bf16 v[8:11], v[148:151], v[208:211], v[8:11]
	v_mfma_f32_16x16x32_bf16 v[4:7], v[156:159], v[208:211], v[4:7]
	v_mfma_f32_16x16x32_bf16 v[56:59], v[152:155], v[188:191], v[56:59]
	v_mfma_f32_16x16x32_bf16 v[52:55], v[160:163], v[188:191], v[52:55]
	v_mfma_f32_16x16x32_bf16 v[40:43], v[152:155], v[196:199], v[40:43]
	v_mfma_f32_16x16x32_bf16 v[36:39], v[160:163], v[196:199], v[36:39]
	v_mfma_f32_16x16x32_bf16 v[24:27], v[152:155], v[204:207], v[24:27]
	v_mfma_f32_16x16x32_bf16 v[20:23], v[160:163], v[204:207], v[20:23]
	v_mfma_f32_16x16x32_bf16 v[8:11], v[152:155], v[212:215], v[8:11]
	v_mfma_f32_16x16x32_bf16 v[4:7], v[160:163], v[212:215], v[4:7]
	s_barrier

	s_add_i32 s10, s10, 2
	s_add_u32 vcc_lo, vcc_lo, 0x100
	s_addc_u32 vcc_hi, vcc_hi, 0
	s_add_u32 s48, s48, 0x100
	s_addc_u32 s49, s49, 0
	s_cmp_gt_u32 s10, 29
	s_cbranch_scc0 .LBB0_790
	s_setprio 0
	v_readlane_b32 s10, v252, 2
	v_readlane_b32 s11, v252, 3

.LBB0_870:
	s_add_u32 s16, s44, 0xfff80080
	s_addc_u32 s17, s45, -1
	s_add_i32 s94, 0, 0x10000
	s_cmp_eq_u32 vcc_lo, 28
	s_cselect_b32 s47, s37, s17
	s_cselect_b32 s46, s88, s16
	s_cselect_b32 s29, s27, s96
	s_cselect_b32 s28, s89, s91
	s_add_i32 s95, 0, 0x14000
	ds_read_b128 v[132:135], v174
	ds_read_b128 v[136:139], v174 offset:1024
	ds_read_b128 v[140:143], v174 offset:2048
	ds_read_b128 v[144:147], v174 offset:3072
	ds_read_b128 v[148:151], v175
	ds_read_b128 v[152:155], v175 offset:1024
	ds_read_b128 v[166:169], v175 offset:2048
	ds_read_b128 v[170:173], v175 offset:3072
	s_add_i32 m0, s48, 0xc000
	ds_read_b128 v[184:187], v229
	ds_read_b128 v[188:191], v229 offset:1024
	ds_read_b128 v[192:195], v229 offset:2048
	ds_read_b128 v[196:199], v229 offset:3072
	ds_read_b128 v[200:203], v229 offset:4096
	ds_read_b128 v[204:207], v229 offset:5120
	ds_read_b128 v[208:211], v229 offset:6144
	ds_read_b128 v[212:215], v229 offset:7168
	global_load_lds_dwordx4 v162, s[44:45]
	s_add_i32 m0, s48, 0xe000
	s_nop 0
	global_load_lds_dwordx4 v164, s[44:45]
	s_waitcnt vmcnt(8) lgkmcnt(0)


	s_barrier
	v_mfma_f32_16x16x32_bf16 v[128:131], v[132:135], v[184:187], v[128:131]
	v_mfma_f32_16x16x32_bf16 v[124:127], v[140:143], v[184:187], v[124:127]
	v_mfma_f32_16x16x32_bf16 v[112:115], v[132:135], v[192:195], v[112:115]
	v_mfma_f32_16x16x32_bf16 v[108:111], v[140:143], v[192:195], v[108:111]
	v_mfma_f32_16x16x32_bf16 v[96:99], v[132:135], v[200:203], v[96:99]
	v_mfma_f32_16x16x32_bf16 v[92:95], v[140:143], v[200:203], v[92:95]
	v_mfma_f32_16x16x32_bf16 v[80:83], v[132:135], v[208:211], v[80:83]
	v_mfma_f32_16x16x32_bf16 v[76:79], v[140:143], v[208:211], v[76:79]
	v_mfma_f32_16x16x32_bf16 v[128:131], v[136:139], v[188:191], v[128:131]
	v_mfma_f32_16x16x32_bf16 v[124:127], v[144:147], v[188:191], v[124:127]
	v_mfma_f32_16x16x32_bf16 v[112:115], v[136:139], v[196:199], v[112:115]
	v_mfma_f32_16x16x32_bf16 v[108:111], v[144:147], v[196:199], v[108:111]
	v_mfma_f32_16x16x32_bf16 v[96:99], v[136:139], v[204:207], v[96:99]
	v_mfma_f32_16x16x32_bf16 v[92:95], v[144:147], v[204:207], v[92:95]
	v_mfma_f32_16x16x32_bf16 v[80:83], v[136:139], v[212:215], v[80:83]
	v_mfma_f32_16x16x32_bf16 v[76:79], v[144:147], v[212:215], v[76:79]
	v_mfma_f32_16x16x32_bf16 v[120:123], v[148:151], v[184:187], v[120:123]
	v_mfma_f32_16x16x32_bf16 v[116:119], v[166:169], v[184:187], v[116:119]
	v_mfma_f32_16x16x32_bf16 v[104:107], v[148:151], v[192:195], v[104:107]
	v_mfma_f32_16x16x32_bf16 v[100:103], v[166:169], v[192:195], v[100:103]
	v_mfma_f32_16x16x32_bf16 v[88:91], v[148:151], v[200:203], v[88:91]
	v_mfma_f32_16x16x32_bf16 v[84:87], v[166:169], v[200:203], v[84:87]
	v_mfma_f32_16x16x32_bf16 v[72:75], v[148:151], v[208:211], v[72:75]
	v_mfma_f32_16x16x32_bf16 v[68:71], v[166:169], v[208:211], v[68:71]
	v_mfma_f32_16x16x32_bf16 v[120:123], v[152:155], v[188:191], v[120:123]
	v_mfma_f32_16x16x32_bf16 v[116:119], v[170:173], v[188:191], v[116:119]
	v_mfma_f32_16x16x32_bf16 v[104:107], v[152:155], v[196:199], v[104:107]
	v_mfma_f32_16x16x32_bf16 v[100:103], v[170:173], v[196:199], v[100:103]
	v_mfma_f32_16x16x32_bf16 v[88:91], v[152:155], v[204:207], v[88:91]
	v_mfma_f32_16x16x32_bf16 v[84:87], v[170:173], v[204:207], v[84:87]
	v_mfma_f32_16x16x32_bf16 v[72:75], v[152:155], v[212:215], v[72:75]
	v_mfma_f32_16x16x32_bf16 v[68:71], v[170:173], v[212:215], v[68:71]
	s_barrier

	s_add_i32 s16, s94, s33
	s_mov_b32 m0, s16
	ds_read_b128 v[184:187], v229 offset:16384
	ds_read_b128 v[188:191], v229 offset:17408
	ds_read_b128 v[192:195], v229 offset:18432
	ds_read_b128 v[196:199], v229 offset:19456
	ds_read_b128 v[200:203], v229 offset:20480
	ds_read_b128 v[204:207], v229 offset:21504
	ds_read_b128 v[208:211], v229 offset:22528
	ds_read_b128 v[212:215], v229 offset:23552
	global_load_lds_dwordx4 v2, s[28:29]
	s_add_i32 m0, s16, 0x2000
	s_add_u32 s16, s28, 0x80000
	s_addc_u32 s17, s29, 0
	s_add_i32 s94, s95, s33
	global_load_lds_dwordx4 v156, s[28:29]
	s_mov_b32 m0, s94
	s_nop 0
	global_load_lds_dwordx4 v2, s[16:17]
	s_add_i32 m0, s94, 0x2000
	s_nop 0
	global_load_lds_dwordx4 v156, s[16:17]
	s_mov_b32 m0, s48
	s_nop 0
	global_load_lds_dwordx4 v160, s[46:47]
	s_mov_b32 m0, s49
	s_nop 0
	global_load_lds_dwordx4 v158, s[46:47]
	s_waitcnt vmcnt(8) lgkmcnt(0)


	s_barrier
	v_mfma_f32_16x16x32_bf16 v[64:67], v[132:135], v[184:187], v[64:67]
	v_mfma_f32_16x16x32_bf16 v[60:63], v[140:143], v[184:187], v[60:63]
	v_mfma_f32_16x16x32_bf16 v[48:51], v[132:135], v[192:195], v[48:51]
	v_mfma_f32_16x16x32_bf16 v[44:47], v[140:143], v[192:195], v[44:47]
	v_mfma_f32_16x16x32_bf16 v[32:35], v[132:135], v[200:203], v[32:35]
	v_mfma_f32_16x16x32_bf16 v[28:31], v[140:143], v[200:203], v[28:31]
	v_mfma_f32_16x16x32_bf16 v[16:19], v[132:135], v[208:211], v[16:19]
	v_mfma_f32_16x16x32_bf16 v[12:15], v[140:143], v[208:211], v[12:15]
	v_mfma_f32_16x16x32_bf16 v[64:67], v[136:139], v[188:191], v[64:67]
	v_mfma_f32_16x16x32_bf16 v[60:63], v[144:147], v[188:191], v[60:63]
	v_mfma_f32_16x16x32_bf16 v[48:51], v[136:139], v[196:199], v[48:51]
	v_mfma_f32_16x16x32_bf16 v[44:47], v[144:147], v[196:199], v[44:47]
	v_mfma_f32_16x16x32_bf16 v[32:35], v[136:139], v[204:207], v[32:35]
	v_mfma_f32_16x16x32_bf16 v[28:31], v[144:147], v[204:207], v[28:31]
	v_mfma_f32_16x16x32_bf16 v[16:19], v[136:139], v[212:215], v[16:19]
	v_mfma_f32_16x16x32_bf16 v[12:15], v[144:147], v[212:215], v[12:15]
	v_mfma_f32_16x16x32_bf16 v[56:59], v[148:151], v[184:187], v[56:59]
	v_mfma_f32_16x16x32_bf16 v[52:55], v[166:169], v[184:187], v[52:55]
	v_mfma_f32_16x16x32_bf16 v[40:43], v[148:151], v[192:195], v[40:43]
	v_mfma_f32_16x16x32_bf16 v[36:39], v[166:169], v[192:195], v[36:39]
	v_mfma_f32_16x16x32_bf16 v[24:27], v[148:151], v[200:203], v[24:27]
	v_mfma_f32_16x16x32_bf16 v[20:23], v[166:169], v[200:203], v[20:23]
	v_mfma_f32_16x16x32_bf16 v[8:11], v[148:151], v[208:211], v[8:11]
	v_mfma_f32_16x16x32_bf16 v[4:7], v[166:169], v[208:211], v[4:7]
	v_mfma_f32_16x16x32_bf16 v[56:59], v[152:155], v[188:191], v[56:59]
	v_mfma_f32_16x16x32_bf16 v[52:55], v[170:173], v[188:191], v[52:55]
	v_mfma_f32_16x16x32_bf16 v[40:43], v[152:155], v[196:199], v[40:43]
	v_mfma_f32_16x16x32_bf16 v[36:39], v[170:173], v[196:199], v[36:39]
	v_mfma_f32_16x16x32_bf16 v[24:27], v[152:155], v[204:207], v[24:27]
	v_mfma_f32_16x16x32_bf16 v[20:23], v[170:173], v[204:207], v[20:23]
	v_mfma_f32_16x16x32_bf16 v[8:11], v[152:155], v[212:215], v[8:11]
	v_mfma_f32_16x16x32_bf16 v[4:7], v[170:173], v[212:215], v[4:7]
	s_barrier

	s_add_i32 s94, 0, 0x18000
	s_add_i32 s95, 0, 0x1c000
	ds_read_b128 v[132:135], v176
	ds_read_b128 v[136:139], v176 offset:1024
	ds_read_b128 v[140:143], v176 offset:2048
	ds_read_b128 v[144:147], v176 offset:3072
	ds_read_b128 v[148:151], v177
	ds_read_b128 v[152:155], v177 offset:1024
	ds_read_b128 v[166:169], v177 offset:2048
	ds_read_b128 v[170:173], v177 offset:3072
	s_add_u32 s16, s46, 0x80000
	s_addc_u32 s17, s47, 0
	s_mov_b32 m0, s50
	ds_read_b128 v[184:187], v229 offset:32768
	ds_read_b128 v[188:191], v229 offset:33792
	ds_read_b128 v[192:195], v229 offset:34816
	ds_read_b128 v[196:199], v229 offset:35840
	ds_read_b128 v[200:203], v229 offset:36864
	ds_read_b128 v[204:207], v229 offset:37888
	ds_read_b128 v[208:211], v229 offset:38912
	ds_read_b128 v[212:215], v229 offset:39936
	global_load_lds_dwordx4 v160, s[16:17]
	s_mov_b32 m0, s51
	s_nop 0
	global_load_lds_dwordx4 v158, s[16:17]
	s_waitcnt vmcnt(8) lgkmcnt(0)


	s_barrier
	v_mfma_f32_16x16x32_bf16 v[128:131], v[132:135], v[184:187], v[128:131]
	v_mfma_f32_16x16x32_bf16 v[124:127], v[140:143], v[184:187], v[124:127]
	v_mfma_f32_16x16x32_bf16 v[112:115], v[132:135], v[192:195], v[112:115]
	v_mfma_f32_16x16x32_bf16 v[108:111], v[140:143], v[192:195], v[108:111]
	v_mfma_f32_16x16x32_bf16 v[96:99], v[132:135], v[200:203], v[96:99]
	v_mfma_f32_16x16x32_bf16 v[92:95], v[140:143], v[200:203], v[92:95]
	v_mfma_f32_16x16x32_bf16 v[80:83], v[132:135], v[208:211], v[80:83]
	v_mfma_f32_16x16x32_bf16 v[76:79], v[140:143], v[208:211], v[76:79]
	v_mfma_f32_16x16x32_bf16 v[128:131], v[136:139], v[188:191], v[128:131]
	v_mfma_f32_16x16x32_bf16 v[124:127], v[144:147], v[188:191], v[124:127]
	v_mfma_f32_16x16x32_bf16 v[112:115], v[136:139], v[196:199], v[112:115]
	v_mfma_f32_16x16x32_bf16 v[108:111], v[144:147], v[196:199], v[108:111]
	v_mfma_f32_16x16x32_bf16 v[96:99], v[136:139], v[204:207], v[96:99]
	v_mfma_f32_16x16x32_bf16 v[92:95], v[144:147], v[204:207], v[92:95]
	v_mfma_f32_16x16x32_bf16 v[80:83], v[136:139], v[212:215], v[80:83]
	v_mfma_f32_16x16x32_bf16 v[76:79], v[144:147], v[212:215], v[76:79]
	v_mfma_f32_16x16x32_bf16 v[120:123], v[148:151], v[184:187], v[120:123]
	v_mfma_f32_16x16x32_bf16 v[116:119], v[166:169], v[184:187], v[116:119]
	v_mfma_f32_16x16x32_bf16 v[104:107], v[148:151], v[192:195], v[104:107]
	v_mfma_f32_16x16x32_bf16 v[100:103], v[166:169], v[192:195], v[100:103]
	v_mfma_f32_16x16x32_bf16 v[88:91], v[148:151], v[200:203], v[88:91]
	v_mfma_f32_16x16x32_bf16 v[84:87], v[166:169], v[200:203], v[84:87]
	v_mfma_f32_16x16x32_bf16 v[72:75], v[148:151], v[208:211], v[72:75]
	v_mfma_f32_16x16x32_bf16 v[68:71], v[166:169], v[208:211], v[68:71]
	v_mfma_f32_16x16x32_bf16 v[120:123], v[152:155], v[188:191], v[120:123]
	v_mfma_f32_16x16x32_bf16 v[116:119], v[170:173], v[188:191], v[116:119]
	v_mfma_f32_16x16x32_bf16 v[104:107], v[152:155], v[196:199], v[104:107]
	v_mfma_f32_16x16x32_bf16 v[100:103], v[170:173], v[196:199], v[100:103]
	v_mfma_f32_16x16x32_bf16 v[88:91], v[152:155], v[204:207], v[88:91]
	v_mfma_f32_16x16x32_bf16 v[84:87], v[170:173], v[204:207], v[84:87]
	v_mfma_f32_16x16x32_bf16 v[72:75], v[152:155], v[212:215], v[72:75]
	v_mfma_f32_16x16x32_bf16 v[68:71], v[170:173], v[212:215], v[68:71]
	s_barrier

	s_add_i32 s16, s94, s33
	s_mov_b32 m0, s16
	ds_read_b128 v[184:187], v229 offset:49152
	ds_read_b128 v[188:191], v229 offset:50176
	ds_read_b128 v[192:195], v229 offset:51200
	ds_read_b128 v[196:199], v229 offset:52224
	ds_read_b128 v[200:203], v229 offset:53248
	ds_read_b128 v[204:207], v229 offset:54272
	ds_read_b128 v[208:211], v229 offset:55296
	ds_read_b128 v[212:215], v229 offset:56320
	s_add_u32 s100, s28, s24
	s_addc_u32 s101, s29, s25
	global_load_lds_dwordx4 v2, s[100:101]
	s_add_i32 m0, s16, 0x2000
	s_add_u32 s16, s28, 0x80080
	s_addc_u32 s17, s29, 0
	s_add_i32 s28, s95, s33
	global_load_lds_dwordx4 v156, s[100:101]
	s_mov_b32 m0, s28
	s_nop 0
	global_load_lds_dwordx4 v2, s[16:17]
	s_add_i32 m0, s28, 0x2000
	s_nop 0
	global_load_lds_dwordx4 v156, s[16:17]
	s_mov_b32 m0, s72
	s_nop 0
	s_add_u32 s100, s46, s24
	s_addc_u32 s101, s47, s25
	global_load_lds_dwordx4 v160, s[100:101]
	s_mov_b32 m0, s73
	s_nop 0
	global_load_lds_dwordx4 v158, s[100:101]
	s_waitcnt vmcnt(8) lgkmcnt(0)


	s_barrier
	v_mfma_f32_16x16x32_bf16 v[64:67], v[132:135], v[184:187], v[64:67]
	v_mfma_f32_16x16x32_bf16 v[60:63], v[140:143], v[184:187], v[60:63]
	v_mfma_f32_16x16x32_bf16 v[48:51], v[132:135], v[192:195], v[48:51]
	v_mfma_f32_16x16x32_bf16 v[44:47], v[140:143], v[192:195], v[44:47]
	v_mfma_f32_16x16x32_bf16 v[32:35], v[132:135], v[200:203], v[32:35]
	v_mfma_f32_16x16x32_bf16 v[28:31], v[140:143], v[200:203], v[28:31]
	v_mfma_f32_16x16x32_bf16 v[16:19], v[132:135], v[208:211], v[16:19]
	v_mfma_f32_16x16x32_bf16 v[12:15], v[140:143], v[208:211], v[12:15]
	v_mfma_f32_16x16x32_bf16 v[64:67], v[136:139], v[188:191], v[64:67]
	v_mfma_f32_16x16x32_bf16 v[60:63], v[144:147], v[188:191], v[60:63]
	v_mfma_f32_16x16x32_bf16 v[48:51], v[136:139], v[196:199], v[48:51]
	v_mfma_f32_16x16x32_bf16 v[44:47], v[144:147], v[196:199], v[44:47]
	v_mfma_f32_16x16x32_bf16 v[32:35], v[136:139], v[204:207], v[32:35]
	v_mfma_f32_16x16x32_bf16 v[28:31], v[144:147], v[204:207], v[28:31]
	v_mfma_f32_16x16x32_bf16 v[16:19], v[136:139], v[212:215], v[16:19]
	v_mfma_f32_16x16x32_bf16 v[12:15], v[144:147], v[212:215], v[12:15]
	v_mfma_f32_16x16x32_bf16 v[56:59], v[148:151], v[184:187], v[56:59]
	v_mfma_f32_16x16x32_bf16 v[52:55], v[166:169], v[184:187], v[52:55]
	v_mfma_f32_16x16x32_bf16 v[40:43], v[148:151], v[192:195], v[40:43]
	v_mfma_f32_16x16x32_bf16 v[36:39], v[166:169], v[192:195], v[36:39]
	v_mfma_f32_16x16x32_bf16 v[24:27], v[148:151], v[200:203], v[24:27]
	v_mfma_f32_16x16x32_bf16 v[20:23], v[166:169], v[200:203], v[20:23]
	v_mfma_f32_16x16x32_bf16 v[8:11], v[148:151], v[208:211], v[8:11]
	v_mfma_f32_16x16x32_bf16 v[4:7], v[166:169], v[208:211], v[4:7]
	v_mfma_f32_16x16x32_bf16 v[56:59], v[152:155], v[188:191], v[56:59]
	v_mfma_f32_16x16x32_bf16 v[52:55], v[170:173], v[188:191], v[52:55]
	v_mfma_f32_16x16x32_bf16 v[40:43], v[152:155], v[196:199], v[40:43]
	v_mfma_f32_16x16x32_bf16 v[36:39], v[170:173], v[196:199], v[36:39]
	v_mfma_f32_16x16x32_bf16 v[24:27], v[152:155], v[204:207], v[24:27]
	v_mfma_f32_16x16x32_bf16 v[20:23], v[170:173], v[204:207], v[20:23]
	v_mfma_f32_16x16x32_bf16 v[8:11], v[152:155], v[212:215], v[8:11]
	v_mfma_f32_16x16x32_bf16 v[4:7], v[170:173], v[212:215], v[4:7]
	s_barrier

	s_add_i32 vcc_lo, vcc_lo, 2
	s_add_u32 s44, s44, 0x100
	s_addc_u32 s45, s45, 0
	s_add_u32 s91, s91, 0x100
	s_addc_u32 s96, s96, 0
	s_cmp_gt_u32 vcc_lo, 29
	s_cbranch_scc0 .LBB0_870
	s_setprio 0

.LBB0_1035:
	s_add_u32 s46, s50, 0x100
	s_addc_u32 s47, s51, 0
	s_add_i32 s16, 0, 0x10000
	s_cmpk_eq_i32 s48, 0x54
	s_cselect_b32 s73, s23, s47
	s_cselect_b32 s72, s22, s46
	s_cselect_b32 s29, s27, vcc_hi
	s_cselect_b32 s28, s26, vcc_lo
	s_add_i32 s49, 0, 0x14000
	ds_read_b128 v[132:135], v174
	ds_read_b128 v[136:139], v174 offset:1024
	ds_read_b128 v[140:143], v174 offset:2048
	ds_read_b128 v[144:147], v174 offset:3072
	ds_read_b128 v[148:151], v175
	ds_read_b128 v[152:155], v175 offset:1024
	ds_read_b128 v[156:159], v175 offset:2048
	ds_read_b128 v[160:163], v175 offset:3072
	s_add_i32 m0, s77, 0xc000
	ds_read_b128 v[164:167], v246
	ds_read_b128 v[188:191], v246 offset:1024
	ds_read_b128 v[192:195], v246 offset:2048
	ds_read_b128 v[196:199], v246 offset:3072
	ds_read_b128 v[200:203], v246 offset:4096
	ds_read_b128 v[204:207], v246 offset:5120
	ds_read_b128 v[208:211], v246 offset:6144
	ds_read_b128 v[212:215], v246 offset:7168
	global_load_lds_dwordx4 v184, s[50:51]
	s_add_i32 m0, s77, 0xe000
	s_nop 0
	global_load_lds_dwordx4 v186, s[50:51]
	s_waitcnt vmcnt(8) lgkmcnt(0)


	s_barrier
	v_mfma_f32_16x16x32_bf16 v[128:131], v[132:135], v[164:167], v[128:131]
	v_mfma_f32_16x16x32_bf16 v[124:127], v[140:143], v[164:167], v[124:127]
	v_mfma_f32_16x16x32_bf16 v[112:115], v[132:135], v[192:195], v[112:115]
	v_mfma_f32_16x16x32_bf16 v[108:111], v[140:143], v[192:195], v[108:111]
	v_mfma_f32_16x16x32_bf16 v[96:99], v[132:135], v[200:203], v[96:99]
	v_mfma_f32_16x16x32_bf16 v[92:95], v[140:143], v[200:203], v[92:95]
	v_mfma_f32_16x16x32_bf16 v[80:83], v[132:135], v[208:211], v[80:83]
	v_mfma_f32_16x16x32_bf16 v[76:79], v[140:143], v[208:211], v[76:79]
	v_mfma_f32_16x16x32_bf16 v[128:131], v[136:139], v[188:191], v[128:131]
	v_mfma_f32_16x16x32_bf16 v[124:127], v[144:147], v[188:191], v[124:127]
	v_mfma_f32_16x16x32_bf16 v[112:115], v[136:139], v[196:199], v[112:115]
	v_mfma_f32_16x16x32_bf16 v[108:111], v[144:147], v[196:199], v[108:111]
	v_mfma_f32_16x16x32_bf16 v[96:99], v[136:139], v[204:207], v[96:99]
	v_mfma_f32_16x16x32_bf16 v[92:95], v[144:147], v[204:207], v[92:95]
	v_mfma_f32_16x16x32_bf16 v[80:83], v[136:139], v[212:215], v[80:83]
	v_mfma_f32_16x16x32_bf16 v[76:79], v[144:147], v[212:215], v[76:79]
	v_mfma_f32_16x16x32_bf16 v[120:123], v[148:151], v[164:167], v[120:123]
	v_mfma_f32_16x16x32_bf16 v[116:119], v[156:159], v[164:167], v[116:119]
	v_mfma_f32_16x16x32_bf16 v[104:107], v[148:151], v[192:195], v[104:107]
	v_mfma_f32_16x16x32_bf16 v[100:103], v[156:159], v[192:195], v[100:103]
	v_mfma_f32_16x16x32_bf16 v[88:91], v[148:151], v[200:203], v[88:91]
	v_mfma_f32_16x16x32_bf16 v[84:87], v[156:159], v[200:203], v[84:87]
	v_mfma_f32_16x16x32_bf16 v[72:75], v[148:151], v[208:211], v[72:75]
	v_mfma_f32_16x16x32_bf16 v[68:71], v[156:159], v[208:211], v[68:71]
	v_mfma_f32_16x16x32_bf16 v[120:123], v[152:155], v[188:191], v[120:123]
	v_mfma_f32_16x16x32_bf16 v[116:119], v[160:163], v[188:191], v[116:119]
	v_mfma_f32_16x16x32_bf16 v[104:107], v[152:155], v[196:199], v[104:107]
	v_mfma_f32_16x16x32_bf16 v[100:103], v[160:163], v[196:199], v[100:103]
	v_mfma_f32_16x16x32_bf16 v[88:91], v[152:155], v[204:207], v[88:91]
	v_mfma_f32_16x16x32_bf16 v[84:87], v[160:163], v[204:207], v[84:87]
	v_mfma_f32_16x16x32_bf16 v[72:75], v[152:155], v[212:215], v[72:75]
	v_mfma_f32_16x16x32_bf16 v[68:71], v[160:163], v[212:215], v[68:71]
	s_barrier

	s_add_i32 s16, s16, s74
	s_mov_b32 m0, s16
	ds_read_b128 v[164:167], v246 offset:16384
	ds_read_b128 v[188:191], v246 offset:17408
	ds_read_b128 v[192:195], v246 offset:18432
	ds_read_b128 v[196:199], v246 offset:19456
	ds_read_b128 v[200:203], v246 offset:20480
	ds_read_b128 v[204:207], v246 offset:21504
	ds_read_b128 v[208:211], v246 offset:22528
	ds_read_b128 v[212:215], v246 offset:23552
	global_load_lds_dwordx4 v2, s[28:29]
	s_add_i32 m0, s16, 0x2000
	s_add_u32 s16, s28, 0x58000
	s_addc_u32 s17, s29, 0
	s_add_i32 s49, s49, s74
	global_load_lds_dwordx4 v168, s[28:29]
	s_mov_b32 m0, s49
	s_nop 0
	global_load_lds_dwordx4 v2, s[16:17]
	s_add_i32 m0, s49, 0x2000
	s_nop 0
	global_load_lds_dwordx4 v168, s[16:17]
	s_mov_b32 m0, s77
	s_nop 0
	global_load_lds_dwordx4 v172, s[72:73]
	s_mov_b32 m0, s78
	s_nop 0
	global_load_lds_dwordx4 v170, s[72:73]
	s_waitcnt vmcnt(8) lgkmcnt(0)


	s_barrier
	v_mfma_f32_16x16x32_bf16 v[64:67], v[132:135], v[164:167], v[64:67]
	v_mfma_f32_16x16x32_bf16 v[60:63], v[140:143], v[164:167], v[60:63]
	v_mfma_f32_16x16x32_bf16 v[48:51], v[132:135], v[192:195], v[48:51]
	v_mfma_f32_16x16x32_bf16 v[44:47], v[140:143], v[192:195], v[44:47]
	v_mfma_f32_16x16x32_bf16 v[32:35], v[132:135], v[200:203], v[32:35]
	v_mfma_f32_16x16x32_bf16 v[28:31], v[140:143], v[200:203], v[28:31]
	v_mfma_f32_16x16x32_bf16 v[16:19], v[132:135], v[208:211], v[16:19]
	v_mfma_f32_16x16x32_bf16 v[12:15], v[140:143], v[208:211], v[12:15]
	v_mfma_f32_16x16x32_bf16 v[64:67], v[136:139], v[188:191], v[64:67]
	v_mfma_f32_16x16x32_bf16 v[60:63], v[144:147], v[188:191], v[60:63]
	v_mfma_f32_16x16x32_bf16 v[48:51], v[136:139], v[196:199], v[48:51]
	v_mfma_f32_16x16x32_bf16 v[44:47], v[144:147], v[196:199], v[44:47]
	v_mfma_f32_16x16x32_bf16 v[32:35], v[136:139], v[204:207], v[32:35]
	v_mfma_f32_16x16x32_bf16 v[28:31], v[144:147], v[204:207], v[28:31]
	v_mfma_f32_16x16x32_bf16 v[16:19], v[136:139], v[212:215], v[16:19]
	v_mfma_f32_16x16x32_bf16 v[12:15], v[144:147], v[212:215], v[12:15]
	v_mfma_f32_16x16x32_bf16 v[56:59], v[148:151], v[164:167], v[56:59]
	v_mfma_f32_16x16x32_bf16 v[52:55], v[156:159], v[164:167], v[52:55]
	v_mfma_f32_16x16x32_bf16 v[40:43], v[148:151], v[192:195], v[40:43]
	v_mfma_f32_16x16x32_bf16 v[36:39], v[156:159], v[192:195], v[36:39]
	v_mfma_f32_16x16x32_bf16 v[24:27], v[148:151], v[200:203], v[24:27]
	v_mfma_f32_16x16x32_bf16 v[20:23], v[156:159], v[200:203], v[20:23]
	v_mfma_f32_16x16x32_bf16 v[8:11], v[148:151], v[208:211], v[8:11]
	v_mfma_f32_16x16x32_bf16 v[4:7], v[156:159], v[208:211], v[4:7]
	v_mfma_f32_16x16x32_bf16 v[56:59], v[152:155], v[188:191], v[56:59]
	v_mfma_f32_16x16x32_bf16 v[52:55], v[160:163], v[188:191], v[52:55]
	v_mfma_f32_16x16x32_bf16 v[40:43], v[152:155], v[196:199], v[40:43]
	v_mfma_f32_16x16x32_bf16 v[36:39], v[160:163], v[196:199], v[36:39]
	v_mfma_f32_16x16x32_bf16 v[24:27], v[152:155], v[204:207], v[24:27]
	v_mfma_f32_16x16x32_bf16 v[20:23], v[160:163], v[204:207], v[20:23]
	v_mfma_f32_16x16x32_bf16 v[8:11], v[152:155], v[212:215], v[8:11]
	v_mfma_f32_16x16x32_bf16 v[4:7], v[160:163], v[212:215], v[4:7]
	s_barrier

	s_add_i32 s49, 0, 0x18000
	s_add_i32 s50, 0, 0x1c000
	ds_read_b128 v[132:135], v176
	ds_read_b128 v[136:139], v176 offset:1024
	ds_read_b128 v[140:143], v176 offset:2048
	ds_read_b128 v[144:147], v176 offset:3072
	ds_read_b128 v[148:151], v177
	ds_read_b128 v[152:155], v177 offset:1024
	ds_read_b128 v[156:159], v177 offset:2048
	ds_read_b128 v[160:163], v177 offset:3072
	s_add_u32 s16, s72, 0x160000
	s_addc_u32 s17, s73, 0
	s_mov_b32 m0, s18
	ds_read_b128 v[164:167], v246 offset:32768
	ds_read_b128 v[188:191], v246 offset:33792
	ds_read_b128 v[192:195], v246 offset:34816
	ds_read_b128 v[196:199], v246 offset:35840
	ds_read_b128 v[200:203], v246 offset:36864
	ds_read_b128 v[204:207], v246 offset:37888
	ds_read_b128 v[208:211], v246 offset:38912
	ds_read_b128 v[212:215], v246 offset:39936
	global_load_lds_dwordx4 v172, s[16:17]
	s_mov_b32 m0, s19
	s_nop 0
	global_load_lds_dwordx4 v170, s[16:17]
	s_waitcnt vmcnt(8) lgkmcnt(0)


	s_barrier
	v_mfma_f32_16x16x32_bf16 v[128:131], v[132:135], v[164:167], v[128:131]
	v_mfma_f32_16x16x32_bf16 v[124:127], v[140:143], v[164:167], v[124:127]
	v_mfma_f32_16x16x32_bf16 v[112:115], v[132:135], v[192:195], v[112:115]
	v_mfma_f32_16x16x32_bf16 v[108:111], v[140:143], v[192:195], v[108:111]
	v_mfma_f32_16x16x32_bf16 v[96:99], v[132:135], v[200:203], v[96:99]
	v_mfma_f32_16x16x32_bf16 v[92:95], v[140:143], v[200:203], v[92:95]
	v_mfma_f32_16x16x32_bf16 v[80:83], v[132:135], v[208:211], v[80:83]
	v_mfma_f32_16x16x32_bf16 v[76:79], v[140:143], v[208:211], v[76:79]
	v_mfma_f32_16x16x32_bf16 v[128:131], v[136:139], v[188:191], v[128:131]
	v_mfma_f32_16x16x32_bf16 v[124:127], v[144:147], v[188:191], v[124:127]
	v_mfma_f32_16x16x32_bf16 v[112:115], v[136:139], v[196:199], v[112:115]
	v_mfma_f32_16x16x32_bf16 v[108:111], v[144:147], v[196:199], v[108:111]
	v_mfma_f32_16x16x32_bf16 v[96:99], v[136:139], v[204:207], v[96:99]
	v_mfma_f32_16x16x32_bf16 v[92:95], v[144:147], v[204:207], v[92:95]
	v_mfma_f32_16x16x32_bf16 v[80:83], v[136:139], v[212:215], v[80:83]
	v_mfma_f32_16x16x32_bf16 v[76:79], v[144:147], v[212:215], v[76:79]
	v_mfma_f32_16x16x32_bf16 v[120:123], v[148:151], v[164:167], v[120:123]
	v_mfma_f32_16x16x32_bf16 v[116:119], v[156:159], v[164:167], v[116:119]
	v_mfma_f32_16x16x32_bf16 v[104:107], v[148:151], v[192:195], v[104:107]
	v_mfma_f32_16x16x32_bf16 v[100:103], v[156:159], v[192:195], v[100:103]
	v_mfma_f32_16x16x32_bf16 v[88:91], v[148:151], v[200:203], v[88:91]
	v_mfma_f32_16x16x32_bf16 v[84:87], v[156:159], v[200:203], v[84:87]
	v_mfma_f32_16x16x32_bf16 v[72:75], v[148:151], v[208:211], v[72:75]
	v_mfma_f32_16x16x32_bf16 v[68:71], v[156:159], v[208:211], v[68:71]
	v_mfma_f32_16x16x32_bf16 v[120:123], v[152:155], v[188:191], v[120:123]
	v_mfma_f32_16x16x32_bf16 v[116:119], v[160:163], v[188:191], v[116:119]
	v_mfma_f32_16x16x32_bf16 v[104:107], v[152:155], v[196:199], v[104:107]
	v_mfma_f32_16x16x32_bf16 v[100:103], v[160:163], v[196:199], v[100:103]
	v_mfma_f32_16x16x32_bf16 v[88:91], v[152:155], v[204:207], v[88:91]
	v_mfma_f32_16x16x32_bf16 v[84:87], v[160:163], v[204:207], v[84:87]
	v_mfma_f32_16x16x32_bf16 v[72:75], v[152:155], v[212:215], v[72:75]
	v_mfma_f32_16x16x32_bf16 v[68:71], v[160:163], v[212:215], v[68:71]
	s_barrier

	s_add_i32 s16, s49, s74
	s_mov_b32 m0, s16
	ds_read_b128 v[164:167], v246 offset:49152
	ds_read_b128 v[188:191], v246 offset:50176
	ds_read_b128 v[192:195], v246 offset:51200
	ds_read_b128 v[196:199], v246 offset:52224
	ds_read_b128 v[200:203], v246 offset:53248
	ds_read_b128 v[204:207], v246 offset:54272
	ds_read_b128 v[208:211], v246 offset:55296
	ds_read_b128 v[212:215], v246 offset:56320
	s_add_u32 s100, s28, s24
	s_addc_u32 s101, s29, s25
	global_load_lds_dwordx4 v2, s[100:101]
	s_add_i32 m0, s16, 0x2000
	s_add_u32 s16, s28, 0x58080
	s_addc_u32 s17, s29, 0
	s_add_i32 s28, s50, s74
	global_load_lds_dwordx4 v168, s[100:101]
	s_mov_b32 m0, s28
	s_nop 0
	global_load_lds_dwordx4 v2, s[16:17]
	s_add_i32 m0, s28, 0x2000
	s_nop 0
	global_load_lds_dwordx4 v168, s[16:17]
	s_mov_b32 m0, s96
	s_nop 0
	s_add_u32 s100, s72, s24
	s_addc_u32 s101, s73, s25
	global_load_lds_dwordx4 v172, s[100:101]
	s_mov_b32 m0, s3
	s_nop 0
	global_load_lds_dwordx4 v170, s[100:101]
	s_waitcnt vmcnt(8) lgkmcnt(0)


	s_barrier
	v_mfma_f32_16x16x32_bf16 v[64:67], v[132:135], v[164:167], v[64:67]
	v_mfma_f32_16x16x32_bf16 v[60:63], v[140:143], v[164:167], v[60:63]
	v_mfma_f32_16x16x32_bf16 v[48:51], v[132:135], v[192:195], v[48:51]
	v_mfma_f32_16x16x32_bf16 v[44:47], v[140:143], v[192:195], v[44:47]
	v_mfma_f32_16x16x32_bf16 v[32:35], v[132:135], v[200:203], v[32:35]
	v_mfma_f32_16x16x32_bf16 v[28:31], v[140:143], v[200:203], v[28:31]
	v_mfma_f32_16x16x32_bf16 v[16:19], v[132:135], v[208:211], v[16:19]
	v_mfma_f32_16x16x32_bf16 v[12:15], v[140:143], v[208:211], v[12:15]
	v_mfma_f32_16x16x32_bf16 v[64:67], v[136:139], v[188:191], v[64:67]
	v_mfma_f32_16x16x32_bf16 v[60:63], v[144:147], v[188:191], v[60:63]
	v_mfma_f32_16x16x32_bf16 v[48:51], v[136:139], v[196:199], v[48:51]
	v_mfma_f32_16x16x32_bf16 v[44:47], v[144:147], v[196:199], v[44:47]
	v_mfma_f32_16x16x32_bf16 v[32:35], v[136:139], v[204:207], v[32:35]
	v_mfma_f32_16x16x32_bf16 v[28:31], v[144:147], v[204:207], v[28:31]
	v_mfma_f32_16x16x32_bf16 v[16:19], v[136:139], v[212:215], v[16:19]
	v_mfma_f32_16x16x32_bf16 v[12:15], v[144:147], v[212:215], v[12:15]
	v_mfma_f32_16x16x32_bf16 v[56:59], v[148:151], v[164:167], v[56:59]
	v_mfma_f32_16x16x32_bf16 v[52:55], v[156:159], v[164:167], v[52:55]
	v_mfma_f32_16x16x32_bf16 v[40:43], v[148:151], v[192:195], v[40:43]
	v_mfma_f32_16x16x32_bf16 v[36:39], v[156:159], v[192:195], v[36:39]
	v_mfma_f32_16x16x32_bf16 v[24:27], v[148:151], v[200:203], v[24:27]
	v_mfma_f32_16x16x32_bf16 v[20:23], v[156:159], v[200:203], v[20:23]
	v_mfma_f32_16x16x32_bf16 v[8:11], v[148:151], v[208:211], v[8:11]
	v_mfma_f32_16x16x32_bf16 v[4:7], v[156:159], v[208:211], v[4:7]
	v_mfma_f32_16x16x32_bf16 v[56:59], v[152:155], v[188:191], v[56:59]
	v_mfma_f32_16x16x32_bf16 v[52:55], v[160:163], v[188:191], v[52:55]
	v_mfma_f32_16x16x32_bf16 v[40:43], v[152:155], v[196:199], v[40:43]
	v_mfma_f32_16x16x32_bf16 v[36:39], v[160:163], v[196:199], v[36:39]
	v_mfma_f32_16x16x32_bf16 v[24:27], v[152:155], v[204:207], v[24:27]
	v_mfma_f32_16x16x32_bf16 v[20:23], v[160:163], v[204:207], v[20:23]
	v_mfma_f32_16x16x32_bf16 v[8:11], v[152:155], v[212:215], v[8:11]
	v_mfma_f32_16x16x32_bf16 v[4:7], v[160:163], v[212:215], v[4:7]
	s_barrier

	s_add_i32 s48, s48, 2
	s_add_u32 vcc_lo, vcc_lo, 0x100
	s_addc_u32 vcc_hi, vcc_hi, 0
	s_cmpk_gt_u32 s48, 0x55
	s_mov_b64 s[50:51], s[46:47]
	s_cbranch_scc0 .LBB0_1035
	s_setprio 0
	v_readlane_b32 s16, v252, 12
	v_readlane_b32 s17, v252, 13
